# xattn: first three Q-fragment loads issued before the K-staged barrier (latency overlaps the barrier wait)
# speedup vs baseline: 1.0019x; 1.0019x over previous
.LBB0_759:
	s_lshl_b32 s4, s53, 2
	s_or_b32 s54, s4, s52
	s_ashr_i32 s4, s54, 6
	s_ashr_i32 s5, s4, 31
	s_and_b32 s56, s52, 3
	s_lshl_b64 s[46:47], s[4:5], 20
	v_lshl_add_u64 v[0:1], v[150:151], 0, s[46:47]
	s_lshl_b32 s10, s56, 9
	v_lshl_add_u64 v[0:1], v[0:1], 0, s[10:11]
	v_readfirstlane_b32 s46, v223
	v_lshl_add_u64 v[160:161], v[0:1], 0, v[148:149]
	s_lshr_b32 s58, s46, 1
	s_lshl_b32 s59, s54, 6
	v_add_co_u32_e32 v168, vcc, s34, v160
	s_and_b32 s54, s58, 0x7fffffe0
	s_and_b32 s58, s59, 0xf00
	v_addc_co_u32_e32 v169, vcc, 0, v161, vcc
	s_lshl_b64 s[4:5], s[4:5], 12
	v_or_b32_e32 v66, s58, v176
	v_add_co_u32_e32 v164, vcc, s35, v160
	s_mov_b32 s55, s11
	v_or_b32_e32 v66, s4, v66
	v_mov_b32_e32 v67, s5
	v_addc_co_u32_e32 v165, vcc, 0, v161, vcc
	v_lshl_add_u64 v[66:67], v[66:67], 0, s[54:55]
	v_add_co_u32_e32 v166, vcc, s48, v160
	v_lshlrev_b64 v[68:69], 6, v[66:67]
	v_lshl_add_u64 v[0:1], v[160:161], 0, s[16:17]
	v_lshl_add_u64 v[46:47], v[160:161], 0, s[18:19]
	v_addc_co_u32_e32 v167, vcc, 0, v161, vcc
	v_lshlrev_b64 v[162:163], 11, v[66:67]
	v_lshl_add_u64 v[66:67], s[6:7], 0, v[68:69]
	global_load_dwordx4 v[2:5], v[160:161], off offset:384
	global_load_dwordx4 v[6:9], v[160:161], off offset:256
	global_load_dwordx4 v[10:13], v[160:161], off offset:128
	global_load_dwordx4 v[14:17], v[160:161], off
	global_load_dwordx4 v[18:21], v[0:1], off offset:256
	global_load_dwordx4 v[22:25], v[0:1], off offset:128
	global_load_dwordx4 v[26:29], v[168:169], off
	global_load_dwordx4 v[30:33], v[164:165], off
	global_load_dwordx4 v[34:37], v[46:47], off offset:384
	global_load_dwordx4 v[38:41], v[46:47], off offset:256
	global_load_dwordx4 v[42:45], v[0:1], off offset:384
	s_nop 0
	global_load_dwordx4 v[46:49], v[46:47], off offset:128
	v_lshl_add_u64 v[0:1], v[160:161], 0, s[36:37]
	global_load_dwordx4 v[50:53], v[166:167], off
	global_load_dwordx4 v[54:57], v[0:1], off offset:128
	global_load_dwordx4 v[58:61], v[0:1], off offset:256
	global_load_dwordx4 v[62:65], v[0:1], off offset:384
	s_mov_b32 s57, s11
	s_lshl_b32 s46, s56, 8
	s_lshl_b32 s56, s56, 4
	v_lshl_add_u64 v[68:69], s[8:9], 0, v[68:69]
	global_load_dwordx4 v[136:139], v[66:67], off offset:32
	global_load_dwordx4 v[140:143], v[66:67], off offset:16
	global_load_dwordx4 v[144:147], v[66:67], off
	v_lshl_add_u64 v[68:69], v[68:69], 0, s[56:57]
	global_load_dwordx4 v[132:135], v[66:67], off offset:48
	global_load_dwordx4 v[128:131], v[68:69], off
	v_mov_b32_e32 v0, 0
	v_or_b32_e32 v70, s10, v162
	v_mov_b32_e32 v71, v163
	s_mov_b32 s47, 0
	v_lshl_add_u64 v[170:171], v[152:153], 0, v[70:71]
	s_waitcnt vmcnt(17)
	ds_write_b128 v172, v[14:17]
	ds_write_b128 v172, v[10:13] offset:128
	ds_write_b128 v172, v[6:9] offset:256
	ds_write_b128 v172, v[2:5] offset:384
	s_waitcnt vmcnt(14)
	ds_write_b128 v172, v[26:29] offset:35840
	ds_write_b128 v172, v[22:25] offset:35968
	ds_write_b128 v172, v[18:21] offset:36096
	s_waitcnt vmcnt(10)
	ds_write_b128 v172, v[42:45] offset:36224
	ds_write_b128 v173, v[30:33]
	s_waitcnt vmcnt(9)
	ds_write_b128 v174, v[46:49]
	ds_write_b128 v175, v[38:41]
	ds_write_b128 v179, v[34:37]
	s_waitcnt vmcnt(8)
	ds_write_b128 v182, v[50:53]
	s_waitcnt vmcnt(7)
	ds_write_b128 v183, v[54:57]
	s_waitcnt vmcnt(6)
	ds_write_b128 v184, v[58:61]
	s_waitcnt vmcnt(5)
	ds_write_b128 v185, v[62:65]
	v_add_u32_e32 v181, 0x11800, v211
	v_add_u32_e32 v220, 0x15e00, v211
	v_add_u32_e32 v221, 0x1a400, v211
	v_add_u32_e32 v222, 0x1ea00, v211
	global_load_dwordx4 v[212:215], v[170:171], off offset:-128
	global_load_dwordx4 v[216:219], v[170:171], off offset:-96
	global_load_dwordx4 v[248:251], v[170:171], off offset:-64
	s_waitcnt lgkmcnt(0)
	s_barrier
.LBB0_760:
	ds_read_b128 v[224:227], v211
	ds_read_b128 v[228:231], v211 offset:17920
	ds_read_b128 v[232:235], v211 offset:35840
	ds_read_b128 v[236:239], v211 offset:53760
	ds_read_b128 v[240:243], v181
	ds_read_b128 v[244:247], v220
	s_waitcnt vmcnt(2) lgkmcnt(5)
	v_mfma_f32_32x32x16_bf16 v[112:127], v[224:227], v[212:215], 0
	ds_read_b128 v[224:227], v221
	s_waitcnt lgkmcnt(5)
	v_mfma_f32_32x32x16_bf16 v[96:111], v[228:231], v[212:215], 0
	ds_read_b128 v[228:231], v222
	s_waitcnt lgkmcnt(5)
	v_mfma_f32_32x32x16_bf16 v[80:95], v[232:235], v[212:215], 0
	ds_read_b128 v[232:235], v211 offset:32
	s_waitcnt lgkmcnt(5)
	v_mfma_f32_32x32x16_bf16 v[64:79], v[236:239], v[212:215], 0
	ds_read_b128 v[236:239], v211 offset:17952
	s_waitcnt lgkmcnt(5)
	v_mfma_f32_32x32x16_bf16 v[48:63], v[240:243], v[212:215], 0
	ds_read_b128 v[240:243], v211 offset:35872
	s_waitcnt lgkmcnt(5)
	v_mfma_f32_32x32x16_bf16 v[32:47], v[244:247], v[212:215], 0
	ds_read_b128 v[244:247], v211 offset:53792
	s_waitcnt lgkmcnt(5)
	v_mfma_f32_32x32x16_bf16 v[16:31], v[224:227], v[212:215], 0
	ds_read_b128 v[224:227], v181 offset:32
	s_waitcnt lgkmcnt(5)
	v_mfma_f32_32x32x16_bf16 v[0:15], v[228:231], v[212:215], 0
	ds_read_b128 v[228:231], v220 offset:32
	global_load_dwordx4 v[212:215], v[170:171], off offset:-32
	s_waitcnt vmcnt(2) lgkmcnt(5)
	v_mfma_f32_32x32x16_bf16 v[112:127], v[232:235], v[216:219], v[112:127]
	ds_read_b128 v[232:235], v221 offset:32
	s_waitcnt lgkmcnt(5)
	v_mfma_f32_32x32x16_bf16 v[96:111], v[236:239], v[216:219], v[96:111]
	ds_read_b128 v[236:239], v222 offset:32
	s_waitcnt lgkmcnt(5)
	v_mfma_f32_32x32x16_bf16 v[80:95], v[240:243], v[216:219], v[80:95]
	ds_read_b128 v[240:243], v211 offset:64
	s_waitcnt lgkmcnt(5)
	v_mfma_f32_32x32x16_bf16 v[64:79], v[244:247], v[216:219], v[64:79]
	ds_read_b128 v[244:247], v211 offset:17984
	s_waitcnt lgkmcnt(5)
	v_mfma_f32_32x32x16_bf16 v[48:63], v[224:227], v[216:219], v[48:63]
	ds_read_b128 v[224:227], v211 offset:35904
	s_waitcnt lgkmcnt(5)
	v_mfma_f32_32x32x16_bf16 v[32:47], v[228:231], v[216:219], v[32:47]
	ds_read_b128 v[228:231], v211 offset:53824
	s_waitcnt lgkmcnt(5)
	v_mfma_f32_32x32x16_bf16 v[16:31], v[232:235], v[216:219], v[16:31]
	ds_read_b128 v[232:235], v181 offset:64
	s_waitcnt lgkmcnt(5)
	v_mfma_f32_32x32x16_bf16 v[0:15], v[236:239], v[216:219], v[0:15]
	ds_read_b128 v[236:239], v220 offset:64
	global_load_dwordx4 v[216:219], v[170:171], off
	s_waitcnt vmcnt(2) lgkmcnt(5)
	v_mfma_f32_32x32x16_bf16 v[112:127], v[240:243], v[248:251], v[112:127]
	ds_read_b128 v[240:243], v221 offset:64
	s_waitcnt lgkmcnt(5)
	v_mfma_f32_32x32x16_bf16 v[96:111], v[244:247], v[248:251], v[96:111]
	ds_read_b128 v[244:247], v222 offset:64
	s_waitcnt lgkmcnt(5)
	v_mfma_f32_32x32x16_bf16 v[80:95], v[224:227], v[248:251], v[80:95]
	ds_read_b128 v[224:227], v211 offset:96
	s_waitcnt lgkmcnt(5)
	v_mfma_f32_32x32x16_bf16 v[64:79], v[228:231], v[248:251], v[64:79]
	ds_read_b128 v[228:231], v211 offset:18016
	s_waitcnt lgkmcnt(5)
	v_mfma_f32_32x32x16_bf16 v[48:63], v[232:235], v[248:251], v[48:63]
	ds_read_b128 v[232:235], v211 offset:35936
	s_waitcnt lgkmcnt(5)
	v_mfma_f32_32x32x16_bf16 v[32:47], v[236:239], v[248:251], v[32:47]
	ds_read_b128 v[236:239], v211 offset:53856
	s_waitcnt lgkmcnt(5)
	v_mfma_f32_32x32x16_bf16 v[16:31], v[240:243], v[248:251], v[16:31]
	ds_read_b128 v[240:243], v181 offset:96
	s_waitcnt lgkmcnt(5)
	v_mfma_f32_32x32x16_bf16 v[0:15], v[244:247], v[248:251], v[0:15]
	ds_read_b128 v[244:247], v220 offset:96
	global_load_dwordx4 v[248:251], v[170:171], off offset:32
	s_waitcnt vmcnt(2) lgkmcnt(5)
	v_mfma_f32_32x32x16_bf16 v[112:127], v[224:227], v[212:215], v[112:127]
	ds_read_b128 v[224:227], v221 offset:96
	s_waitcnt lgkmcnt(5)
	v_mfma_f32_32x32x16_bf16 v[96:111], v[228:231], v[212:215], v[96:111]
	ds_read_b128 v[228:231], v222 offset:96
	s_waitcnt lgkmcnt(5)
	v_mfma_f32_32x32x16_bf16 v[80:95], v[232:235], v[212:215], v[80:95]
	ds_read_b128 v[232:235], v211 offset:128
	s_waitcnt lgkmcnt(5)
	v_mfma_f32_32x32x16_bf16 v[64:79], v[236:239], v[212:215], v[64:79]
	ds_read_b128 v[236:239], v211 offset:18048
	s_waitcnt lgkmcnt(5)
	v_mfma_f32_32x32x16_bf16 v[48:63], v[240:243], v[212:215], v[48:63]
	ds_read_b128 v[240:243], v211 offset:35968
	s_waitcnt lgkmcnt(5)
	v_mfma_f32_32x32x16_bf16 v[32:47], v[244:247], v[212:215], v[32:47]
	ds_read_b128 v[244:247], v211 offset:53888
	s_waitcnt lgkmcnt(5)
	v_mfma_f32_32x32x16_bf16 v[16:31], v[224:227], v[212:215], v[16:31]
	ds_read_b128 v[224:227], v181 offset:128
	s_waitcnt lgkmcnt(5)
	v_mfma_f32_32x32x16_bf16 v[0:15], v[228:231], v[212:215], v[0:15]
	ds_read_b128 v[228:231], v220 offset:128
	global_load_dwordx4 v[212:215], v[170:171], off offset:64
	s_waitcnt vmcnt(2) lgkmcnt(5)
	v_mfma_f32_32x32x16_bf16 v[112:127], v[232:235], v[216:219], v[112:127]
	ds_read_b128 v[232:235], v221 offset:128
	s_waitcnt lgkmcnt(5)
	v_mfma_f32_32x32x16_bf16 v[96:111], v[236:239], v[216:219], v[96:111]
	ds_read_b128 v[236:239], v222 offset:128
	s_waitcnt lgkmcnt(5)
	v_mfma_f32_32x32x16_bf16 v[80:95], v[240:243], v[216:219], v[80:95]
	ds_read_b128 v[240:243], v211 offset:160
	s_waitcnt lgkmcnt(5)
	v_mfma_f32_32x32x16_bf16 v[64:79], v[244:247], v[216:219], v[64:79]
	ds_read_b128 v[244:247], v211 offset:18080
	s_waitcnt lgkmcnt(5)
	v_mfma_f32_32x32x16_bf16 v[48:63], v[224:227], v[216:219], v[48:63]
	ds_read_b128 v[224:227], v211 offset:36000
	s_waitcnt lgkmcnt(5)
	v_mfma_f32_32x32x16_bf16 v[32:47], v[228:231], v[216:219], v[32:47]
	ds_read_b128 v[228:231], v211 offset:53920
	s_waitcnt lgkmcnt(5)
	v_mfma_f32_32x32x16_bf16 v[16:31], v[232:235], v[216:219], v[16:31]
	ds_read_b128 v[232:235], v181 offset:160
	s_waitcnt lgkmcnt(5)
	v_mfma_f32_32x32x16_bf16 v[0:15], v[236:239], v[216:219], v[0:15]
	ds_read_b128 v[236:239], v220 offset:160
	global_load_dwordx4 v[216:219], v[170:171], off offset:96
	s_waitcnt vmcnt(2) lgkmcnt(5)
	v_mfma_f32_32x32x16_bf16 v[112:127], v[240:243], v[248:251], v[112:127]
	ds_read_b128 v[240:243], v221 offset:160
	s_waitcnt lgkmcnt(5)
	v_mfma_f32_32x32x16_bf16 v[96:111], v[244:247], v[248:251], v[96:111]
	ds_read_b128 v[244:247], v222 offset:160
	s_waitcnt lgkmcnt(5)
	v_mfma_f32_32x32x16_bf16 v[80:95], v[224:227], v[248:251], v[80:95]
	ds_read_b128 v[224:227], v211 offset:192
	s_waitcnt lgkmcnt(5)
	v_mfma_f32_32x32x16_bf16 v[64:79], v[228:231], v[248:251], v[64:79]
	ds_read_b128 v[228:231], v211 offset:18112
	s_waitcnt lgkmcnt(5)
	v_mfma_f32_32x32x16_bf16 v[48:63], v[232:235], v[248:251], v[48:63]
	ds_read_b128 v[232:235], v211 offset:36032
	s_waitcnt lgkmcnt(5)
	v_mfma_f32_32x32x16_bf16 v[32:47], v[236:239], v[248:251], v[32:47]
	ds_read_b128 v[236:239], v211 offset:53952
	s_waitcnt lgkmcnt(5)
	v_mfma_f32_32x32x16_bf16 v[16:31], v[240:243], v[248:251], v[16:31]
	ds_read_b128 v[240:243], v181 offset:192
	s_waitcnt lgkmcnt(5)
	v_mfma_f32_32x32x16_bf16 v[0:15], v[244:247], v[248:251], v[0:15]
	ds_read_b128 v[244:247], v220 offset:192
	global_load_dwordx4 v[248:251], v[170:171], off offset:128
	s_waitcnt vmcnt(2) lgkmcnt(5)
	v_mfma_f32_32x32x16_bf16 v[112:127], v[224:227], v[212:215], v[112:127]
	ds_read_b128 v[224:227], v221 offset:192
	s_waitcnt lgkmcnt(5)
	v_mfma_f32_32x32x16_bf16 v[96:111], v[228:231], v[212:215], v[96:111]
	ds_read_b128 v[228:231], v222 offset:192
	s_waitcnt lgkmcnt(5)
	v_mfma_f32_32x32x16_bf16 v[80:95], v[232:235], v[212:215], v[80:95]
	ds_read_b128 v[232:235], v211 offset:224
	s_waitcnt lgkmcnt(5)
	v_mfma_f32_32x32x16_bf16 v[64:79], v[236:239], v[212:215], v[64:79]
	ds_read_b128 v[236:239], v211 offset:18144
	s_waitcnt lgkmcnt(5)
	v_mfma_f32_32x32x16_bf16 v[48:63], v[240:243], v[212:215], v[48:63]
	ds_read_b128 v[240:243], v211 offset:36064
	s_waitcnt lgkmcnt(5)
	v_mfma_f32_32x32x16_bf16 v[32:47], v[244:247], v[212:215], v[32:47]
	ds_read_b128 v[244:247], v211 offset:53984
	s_waitcnt lgkmcnt(5)
	v_mfma_f32_32x32x16_bf16 v[16:31], v[224:227], v[212:215], v[16:31]
	ds_read_b128 v[224:227], v181 offset:224
	s_waitcnt lgkmcnt(5)
	v_mfma_f32_32x32x16_bf16 v[0:15], v[228:231], v[212:215], v[0:15]
	ds_read_b128 v[228:231], v220 offset:224
	global_load_dwordx4 v[212:215], v[170:171], off offset:160
	s_waitcnt vmcnt(2) lgkmcnt(5)
	v_mfma_f32_32x32x16_bf16 v[112:127], v[232:235], v[216:219], v[112:127]
	ds_read_b128 v[232:235], v221 offset:224
	s_waitcnt lgkmcnt(5)
	v_mfma_f32_32x32x16_bf16 v[96:111], v[236:239], v[216:219], v[96:111]
	ds_read_b128 v[236:239], v222 offset:224
	s_waitcnt lgkmcnt(5)
	v_mfma_f32_32x32x16_bf16 v[80:95], v[240:243], v[216:219], v[80:95]
	ds_read_b128 v[240:243], v211 offset:256
	s_waitcnt lgkmcnt(5)
	v_mfma_f32_32x32x16_bf16 v[64:79], v[244:247], v[216:219], v[64:79]
	ds_read_b128 v[244:247], v211 offset:18176
	s_waitcnt lgkmcnt(5)
	v_mfma_f32_32x32x16_bf16 v[48:63], v[224:227], v[216:219], v[48:63]
	ds_read_b128 v[224:227], v211 offset:36096
	s_waitcnt lgkmcnt(5)
	v_mfma_f32_32x32x16_bf16 v[32:47], v[228:231], v[216:219], v[32:47]
	ds_read_b128 v[228:231], v211 offset:54016
	s_waitcnt lgkmcnt(5)
	v_mfma_f32_32x32x16_bf16 v[16:31], v[232:235], v[216:219], v[16:31]
	ds_read_b128 v[232:235], v181 offset:256
	s_waitcnt lgkmcnt(5)
	v_mfma_f32_32x32x16_bf16 v[0:15], v[236:239], v[216:219], v[0:15]
	ds_read_b128 v[236:239], v220 offset:256
	global_load_dwordx4 v[216:219], v[170:171], off offset:192
	s_waitcnt vmcnt(2) lgkmcnt(5)
	v_mfma_f32_32x32x16_bf16 v[112:127], v[240:243], v[248:251], v[112:127]
	ds_read_b128 v[240:243], v221 offset:256
	s_waitcnt lgkmcnt(5)
	v_mfma_f32_32x32x16_bf16 v[96:111], v[244:247], v[248:251], v[96:111]
	ds_read_b128 v[244:247], v222 offset:256
	s_waitcnt lgkmcnt(5)
	v_mfma_f32_32x32x16_bf16 v[80:95], v[224:227], v[248:251], v[80:95]
	ds_read_b128 v[224:227], v211 offset:288
	s_waitcnt lgkmcnt(5)
	v_mfma_f32_32x32x16_bf16 v[64:79], v[228:231], v[248:251], v[64:79]
	ds_read_b128 v[228:231], v211 offset:18208
	s_waitcnt lgkmcnt(5)
	v_mfma_f32_32x32x16_bf16 v[48:63], v[232:235], v[248:251], v[48:63]
	ds_read_b128 v[232:235], v211 offset:36128
	s_waitcnt lgkmcnt(5)
	v_mfma_f32_32x32x16_bf16 v[32:47], v[236:239], v[248:251], v[32:47]
	ds_read_b128 v[236:239], v211 offset:54048
	s_waitcnt lgkmcnt(5)
	v_mfma_f32_32x32x16_bf16 v[16:31], v[240:243], v[248:251], v[16:31]
	ds_read_b128 v[240:243], v181 offset:288
	s_waitcnt lgkmcnt(5)
	v_mfma_f32_32x32x16_bf16 v[0:15], v[244:247], v[248:251], v[0:15]
	ds_read_b128 v[244:247], v220 offset:288
	global_load_dwordx4 v[248:251], v[170:171], off offset:224
	s_waitcnt vmcnt(2) lgkmcnt(5)
	v_mfma_f32_32x32x16_bf16 v[112:127], v[224:227], v[212:215], v[112:127]
	ds_read_b128 v[224:227], v221 offset:288
	s_waitcnt lgkmcnt(5)
	v_mfma_f32_32x32x16_bf16 v[96:111], v[228:231], v[212:215], v[96:111]
	ds_read_b128 v[228:231], v222 offset:288
	s_waitcnt lgkmcnt(5)
	v_mfma_f32_32x32x16_bf16 v[80:95], v[232:235], v[212:215], v[80:95]
	ds_read_b128 v[232:235], v211 offset:320
	s_waitcnt lgkmcnt(5)
	v_mfma_f32_32x32x16_bf16 v[64:79], v[236:239], v[212:215], v[64:79]
	ds_read_b128 v[236:239], v211 offset:18240
	s_waitcnt lgkmcnt(5)
	v_mfma_f32_32x32x16_bf16 v[48:63], v[240:243], v[212:215], v[48:63]
	ds_read_b128 v[240:243], v211 offset:36160
	s_waitcnt lgkmcnt(5)
	v_mfma_f32_32x32x16_bf16 v[32:47], v[244:247], v[212:215], v[32:47]
	ds_read_b128 v[244:247], v211 offset:54080
	s_waitcnt lgkmcnt(5)
	v_mfma_f32_32x32x16_bf16 v[16:31], v[224:227], v[212:215], v[16:31]
	ds_read_b128 v[224:227], v181 offset:320
	s_waitcnt lgkmcnt(5)
	v_mfma_f32_32x32x16_bf16 v[0:15], v[228:231], v[212:215], v[0:15]
	ds_read_b128 v[228:231], v220 offset:320
	global_load_dwordx4 v[212:215], v[170:171], off offset:256
	s_waitcnt vmcnt(2) lgkmcnt(5)
	v_mfma_f32_32x32x16_bf16 v[112:127], v[232:235], v[216:219], v[112:127]
	ds_read_b128 v[232:235], v221 offset:320
	s_waitcnt lgkmcnt(5)
	v_mfma_f32_32x32x16_bf16 v[96:111], v[236:239], v[216:219], v[96:111]
	ds_read_b128 v[236:239], v222 offset:320
	s_waitcnt lgkmcnt(5)
	v_mfma_f32_32x32x16_bf16 v[80:95], v[240:243], v[216:219], v[80:95]
	ds_read_b128 v[240:243], v211 offset:352
	s_waitcnt lgkmcnt(5)
	v_mfma_f32_32x32x16_bf16 v[64:79], v[244:247], v[216:219], v[64:79]
	ds_read_b128 v[244:247], v211 offset:18272
	s_waitcnt lgkmcnt(5)
	v_mfma_f32_32x32x16_bf16 v[48:63], v[224:227], v[216:219], v[48:63]
	ds_read_b128 v[224:227], v211 offset:36192
	s_waitcnt lgkmcnt(5)
	v_mfma_f32_32x32x16_bf16 v[32:47], v[228:231], v[216:219], v[32:47]
	ds_read_b128 v[228:231], v211 offset:54112
	s_waitcnt lgkmcnt(5)
	v_mfma_f32_32x32x16_bf16 v[16:31], v[232:235], v[216:219], v[16:31]
	ds_read_b128 v[232:235], v181 offset:352
	s_waitcnt lgkmcnt(5)
	v_mfma_f32_32x32x16_bf16 v[0:15], v[236:239], v[216:219], v[0:15]
	ds_read_b128 v[236:239], v220 offset:352
	global_load_dwordx4 v[216:219], v[170:171], off offset:288
	s_waitcnt vmcnt(2) lgkmcnt(5)
	v_mfma_f32_32x32x16_bf16 v[112:127], v[240:243], v[248:251], v[112:127]
	ds_read_b128 v[240:243], v221 offset:352
	s_waitcnt lgkmcnt(5)
	v_mfma_f32_32x32x16_bf16 v[96:111], v[244:247], v[248:251], v[96:111]
	ds_read_b128 v[244:247], v222 offset:352
	s_waitcnt lgkmcnt(5)
	v_mfma_f32_32x32x16_bf16 v[80:95], v[224:227], v[248:251], v[80:95]
	ds_read_b128 v[224:227], v211 offset:384
	s_waitcnt lgkmcnt(5)
	v_mfma_f32_32x32x16_bf16 v[64:79], v[228:231], v[248:251], v[64:79]
	ds_read_b128 v[228:231], v211 offset:18304
	s_waitcnt lgkmcnt(5)
	v_mfma_f32_32x32x16_bf16 v[48:63], v[232:235], v[248:251], v[48:63]
	ds_read_b128 v[232:235], v211 offset:36224
	s_waitcnt lgkmcnt(5)
	v_mfma_f32_32x32x16_bf16 v[32:47], v[236:239], v[248:251], v[32:47]
	ds_read_b128 v[236:239], v211 offset:54144
	s_waitcnt lgkmcnt(5)
	v_mfma_f32_32x32x16_bf16 v[16:31], v[240:243], v[248:251], v[16:31]
	ds_read_b128 v[240:243], v181 offset:384
	s_waitcnt lgkmcnt(5)
	v_mfma_f32_32x32x16_bf16 v[0:15], v[244:247], v[248:251], v[0:15]
	ds_read_b128 v[244:247], v220 offset:384
	global_load_dwordx4 v[248:251], v[170:171], off offset:320
	s_waitcnt vmcnt(2) lgkmcnt(5)
	v_mfma_f32_32x32x16_bf16 v[112:127], v[224:227], v[212:215], v[112:127]
	ds_read_b128 v[224:227], v221 offset:384
	s_waitcnt lgkmcnt(5)
	v_mfma_f32_32x32x16_bf16 v[96:111], v[228:231], v[212:215], v[96:111]
	ds_read_b128 v[228:231], v222 offset:384
	s_waitcnt lgkmcnt(5)
	v_mfma_f32_32x32x16_bf16 v[80:95], v[232:235], v[212:215], v[80:95]
	ds_read_b128 v[232:235], v211 offset:416
	s_waitcnt lgkmcnt(5)
	v_mfma_f32_32x32x16_bf16 v[64:79], v[236:239], v[212:215], v[64:79]
	ds_read_b128 v[236:239], v211 offset:18336
	s_waitcnt lgkmcnt(5)
	v_mfma_f32_32x32x16_bf16 v[48:63], v[240:243], v[212:215], v[48:63]
	ds_read_b128 v[240:243], v211 offset:36256
	s_waitcnt lgkmcnt(5)
	v_mfma_f32_32x32x16_bf16 v[32:47], v[244:247], v[212:215], v[32:47]
	ds_read_b128 v[244:247], v211 offset:54176
	s_waitcnt lgkmcnt(5)
	v_mfma_f32_32x32x16_bf16 v[16:31], v[224:227], v[212:215], v[16:31]
	ds_read_b128 v[224:227], v181 offset:416
	s_waitcnt lgkmcnt(5)
	v_mfma_f32_32x32x16_bf16 v[0:15], v[228:231], v[212:215], v[0:15]
	ds_read_b128 v[228:231], v220 offset:416
	global_load_dwordx4 v[212:215], v[170:171], off offset:352
	s_waitcnt vmcnt(2) lgkmcnt(5)
	v_mfma_f32_32x32x16_bf16 v[112:127], v[232:235], v[216:219], v[112:127]
	ds_read_b128 v[232:235], v221 offset:416
	s_waitcnt lgkmcnt(5)
	v_mfma_f32_32x32x16_bf16 v[96:111], v[236:239], v[216:219], v[96:111]
	ds_read_b128 v[236:239], v222 offset:416
	s_waitcnt lgkmcnt(5)
	v_mfma_f32_32x32x16_bf16 v[80:95], v[240:243], v[216:219], v[80:95]
	ds_read_b128 v[240:243], v211 offset:448
	s_waitcnt lgkmcnt(5)
	v_mfma_f32_32x32x16_bf16 v[64:79], v[244:247], v[216:219], v[64:79]
	ds_read_b128 v[244:247], v211 offset:18368
	s_waitcnt lgkmcnt(5)
	v_mfma_f32_32x32x16_bf16 v[48:63], v[224:227], v[216:219], v[48:63]
	ds_read_b128 v[224:227], v211 offset:36288
	s_waitcnt lgkmcnt(5)
	v_mfma_f32_32x32x16_bf16 v[32:47], v[228:231], v[216:219], v[32:47]
	ds_read_b128 v[228:231], v211 offset:54208
	s_waitcnt lgkmcnt(5)
	v_mfma_f32_32x32x16_bf16 v[16:31], v[232:235], v[216:219], v[16:31]
	ds_read_b128 v[232:235], v181 offset:448
	s_waitcnt lgkmcnt(5)
	v_mfma_f32_32x32x16_bf16 v[0:15], v[236:239], v[216:219], v[0:15]
	ds_read_b128 v[236:239], v220 offset:448
	s_waitcnt vmcnt(1) lgkmcnt(5)
	v_mfma_f32_32x32x16_bf16 v[112:127], v[240:243], v[248:251], v[112:127]
	ds_read_b128 v[240:243], v221 offset:448
	s_waitcnt lgkmcnt(5)
	v_mfma_f32_32x32x16_bf16 v[96:111], v[244:247], v[248:251], v[96:111]
	ds_read_b128 v[244:247], v222 offset:448
	s_waitcnt lgkmcnt(5)
	v_mfma_f32_32x32x16_bf16 v[80:95], v[224:227], v[248:251], v[80:95]
	ds_read_b128 v[224:227], v211 offset:480
	s_waitcnt lgkmcnt(5)
	v_mfma_f32_32x32x16_bf16 v[64:79], v[228:231], v[248:251], v[64:79]
	ds_read_b128 v[228:231], v211 offset:18400
	s_waitcnt lgkmcnt(5)
	v_mfma_f32_32x32x16_bf16 v[48:63], v[232:235], v[248:251], v[48:63]
	ds_read_b128 v[232:235], v211 offset:36320
	s_waitcnt lgkmcnt(5)
	v_mfma_f32_32x32x16_bf16 v[32:47], v[236:239], v[248:251], v[32:47]
	ds_read_b128 v[236:239], v211 offset:54240
	s_waitcnt lgkmcnt(5)
	v_mfma_f32_32x32x16_bf16 v[16:31], v[240:243], v[248:251], v[16:31]
	ds_read_b128 v[240:243], v181 offset:480
	s_waitcnt lgkmcnt(5)
	v_mfma_f32_32x32x16_bf16 v[0:15], v[244:247], v[248:251], v[0:15]
	ds_read_b128 v[244:247], v220 offset:480
	s_waitcnt vmcnt(0) lgkmcnt(5)
	v_mfma_f32_32x32x16_bf16 v[112:127], v[224:227], v[212:215], v[112:127]
	ds_read_b128 v[224:227], v221 offset:480
	s_waitcnt lgkmcnt(5)
	v_mfma_f32_32x32x16_bf16 v[96:111], v[228:231], v[212:215], v[96:111]
	ds_read_b128 v[228:231], v222 offset:480
	s_waitcnt lgkmcnt(5)
	v_mfma_f32_32x32x16_bf16 v[80:95], v[232:235], v[212:215], v[80:95]
	s_waitcnt lgkmcnt(4)
	v_mfma_f32_32x32x16_bf16 v[64:79], v[236:239], v[212:215], v[64:79]
	s_waitcnt lgkmcnt(3)
	v_mfma_f32_32x32x16_bf16 v[48:63], v[240:243], v[212:215], v[48:63]
	s_waitcnt lgkmcnt(2)
	v_mfma_f32_32x32x16_bf16 v[32:47], v[244:247], v[212:215], v[32:47]
	s_waitcnt lgkmcnt(1)
	v_mfma_f32_32x32x16_bf16 v[16:31], v[224:227], v[212:215], v[16:31]
	s_waitcnt lgkmcnt(0)
	v_mfma_f32_32x32x16_bf16 v[0:15], v[228:231], v[212:215], v[0:15]
	s_movk_i32 s47, 0x200
	v_lshl_add_u64 v[244:245], v[160:161], 0, s[38:39]
	global_load_dwordx4 v[212:215], v[160:161], off offset:2432
	global_load_dwordx4 v[216:219], v[160:161], off offset:2304
	global_load_dwordx4 v[224:227], v[160:161], off offset:2176
	global_load_dwordx4 v[228:231], v[160:161], off offset:2048
	global_load_dwordx4 v[232:235], v[168:169], off offset:2048
	global_load_dwordx4 v[236:239], v[244:245], off offset:384
	global_load_dwordx4 v[240:243], v[244:245], off offset:256
	global_load_dwordx4 v[246:249], v[244:245], off offset:128
	v_mov_b32_e32 v170, v145
	v_mov_b32_e32 v171, v146
	v_mov_b32_e32 v145, v147
	v_mov_b32_e32 v146, v141
	v_mov_b32_e32 v147, v142
	v_mov_b32_e32 v141, v143
	v_pk_add_f32 v[144:145], v[170:171], v[144:145]
	v_pk_add_f32 v[140:141], v[146:147], v[140:141]
	v_pk_add_f32 v[144:145], v[144:145], v[144:145] op_sel:[0,1] op_sel_hi:[1,0]
	v_pk_add_f32 v[140:141], v[140:141], v[140:141] op_sel:[0,1] op_sel_hi:[1,0]
	v_add_f32_e32 v136, v136, v137
	v_add_f32_e32 v138, v138, v139
	v_mov_b32_e32 v145, v132
	v_mov_b32_e32 v141, v133
	v_mov_b32_e32 v137, v134
	v_mov_b32_e32 v139, v135
	v_pk_add_f32 v[132:133], v[144:145], v[140:141]
	v_pk_add_f32 v[134:135], v[136:137], v[138:139]
	s_lshl_b32 s10, s46, 1
	v_pk_add_f32 v[132:133], v[132:133], v[134:135]
	v_mov_b32_e32 v159, v149
	v_add_f32_e32 v132, v132, v133
	v_fmamk_f32 v132, v132, 0x3a800000, v180
	v_cmp_gt_f32_e32 vcc, s49, v132
	v_mul_f32_e32 v133, 0x4b800000, v132
	s_add_i32 s51, s51, 1
	v_cndmask_b32_e32 v132, v132, v133, vcc
	v_rsq_f32_e32 v132, v132
	s_nop 0
	v_mul_f32_e32 v133, 0x45800000, v132
	v_cndmask_b32_e32 v134, v132, v133, vcc
	v_mov_b32_e32 v132, v129
	v_mov_b32_e32 v133, v130
	v_mov_b32_e32 v129, v131
	v_pk_add_f32 v[128:129], v[132:133], v[128:129]
	v_and_b32_e32 v131, 64, v178
	v_add_f32_e32 v128, v128, v129
	v_mul_f32_e32 v129, v134, v134
	v_mul_f32_e32 v128, v128, v129
	v_fmamk_f32 v128, v128, 0x3b800000, v180
	v_cmp_gt_f32_e32 vcc, s49, v128
	v_mul_f32_e32 v129, 0x4b800000, v128
	v_add_u32_e32 v131, 64, v131
	v_cndmask_b32_e32 v128, v128, v129, vcc
	v_rsq_f32_e32 v128, v128
	s_nop 0
	v_mul_f32_e32 v129, 0x45800000, v128
	v_cndmask_b32_e32 v128, v128, v129, vcc
	v_max3_f32 v129, v112, s50, v113
	v_max3_f32 v129, v129, v114, v115
	v_max3_f32 v129, v129, v116, v117
	v_max3_f32 v129, v129, v118, v119
	v_max3_f32 v129, v129, v120, v121
	v_max3_f32 v129, v129, v122, v123
	v_max3_f32 v129, v129, v124, v125
	v_max3_f32 v129, v129, v126, v127
	v_max3_f32 v129, v129, v96, v97
	v_max3_f32 v129, v129, v98, v99
	v_max3_f32 v129, v129, v100, v101
	v_max3_f32 v129, v129, v102, v103
	v_max3_f32 v129, v129, v104, v105
	v_max3_f32 v129, v129, v106, v107
	v_max3_f32 v129, v129, v108, v109
	v_max3_f32 v129, v129, v110, v111
	v_max3_f32 v129, v129, v80, v81
	v_max3_f32 v129, v129, v82, v83
	v_max3_f32 v129, v129, v84, v85
	v_max3_f32 v129, v129, v86, v87
	v_max3_f32 v129, v129, v88, v89
	v_max3_f32 v129, v129, v90, v91
	v_max3_f32 v129, v129, v92, v93
	v_max3_f32 v129, v129, v94, v95
	v_max3_f32 v129, v129, v64, v65
	v_max3_f32 v129, v129, v66, v67
	v_max3_f32 v129, v129, v68, v69
	v_max3_f32 v129, v129, v70, v71
	v_max3_f32 v129, v129, v72, v73
	v_max3_f32 v129, v129, v74, v75
	v_max3_f32 v129, v129, v76, v77
	v_max3_f32 v129, v129, v78, v79
	v_max3_f32 v129, v129, v48, v49
	v_max3_f32 v129, v129, v50, v51
	v_max3_f32 v129, v129, v52, v53
	v_max3_f32 v129, v129, v54, v55
	v_max3_f32 v129, v129, v56, v57
	v_max3_f32 v129, v129, v58, v59
	v_max3_f32 v129, v129, v60, v61
	v_max3_f32 v129, v129, v62, v63
	v_max3_f32 v129, v129, v32, v33
	v_max3_f32 v129, v129, v34, v35
	v_max3_f32 v129, v129, v36, v37
	v_max3_f32 v129, v129, v38, v39
	v_max3_f32 v129, v129, v40, v41
	v_max3_f32 v129, v129, v42, v43
	v_max3_f32 v129, v129, v44, v45
	v_max3_f32 v129, v129, v46, v47
	v_max3_f32 v129, v129, v16, v17
	v_max3_f32 v129, v129, v18, v19
	v_max3_f32 v129, v129, v20, v21
	v_max3_f32 v129, v129, v22, v23
	v_max3_f32 v129, v129, v24, v25
	v_max3_f32 v129, v129, v26, v27
	v_max3_f32 v129, v129, v28, v29
	v_max3_f32 v129, v129, v30, v31
	v_max3_f32 v129, v129, v0, v1
	v_max3_f32 v129, v129, v2, v3
	v_max3_f32 v129, v129, v4, v5
	v_max3_f32 v129, v129, v6, v7
	v_max3_f32 v129, v129, v8, v9
	v_max3_f32 v129, v129, v10, v11
	v_mul_f32_e32 v128, v134, v128
	v_max3_f32 v129, v129, v12, v13
	v_max3_f32 v130, v129, v14, v15
	v_mul_f32_e32 v129, 0x3db8aa3b, v128
	v_xor_b32_e32 v128, 32, v178
	v_cmp_lt_i32_e32 vcc, v128, v131
	v_mul_f32_e32 v130, v129, v130
	s_nop 0
	v_cndmask_b32_e32 v128, v178, v128, vcc
	v_lshlrev_b32_e32 v128, 2, v128
	ds_bpermute_b32 v131, v128, v130
	s_waitcnt lgkmcnt(0)
	v_max_f32_e32 v131, v131, v131
	v_max_f32_e32 v130, v130, v131
	v_fma_f32 v112, v129, v112, -v130
	v_exp_f32_e32 v112, v112
	v_fma_f32 v113, v129, v113, -v130
	v_exp_f32_e32 v113, v113
	v_fma_f32 v114, v129, v114, -v130
	v_exp_f32_e32 v114, v114
	v_fma_f32 v115, v129, v115, -v130
	v_exp_f32_e32 v115, v115
	v_fma_f32 v116, v129, v116, -v130
	v_add_f32_e32 v131, 0, v112
	v_exp_f32_e32 v132, v116
	v_add_f32_e32 v131, v113, v131
	v_add_f32_e32 v131, v114, v131
	v_add_f32_e32 v131, v115, v131
	v_fma_f32 v117, v129, v117, -v130
	v_add_f32_e32 v116, v132, v131
	v_exp_f32_e32 v131, v117
	v_fma_f32 v117, v129, v118, -v130
	v_exp_f32_e32 v133, v117
	v_fma_f32 v117, v129, v119, -v130
	v_exp_f32_e32 v119, v117
	v_fma_f32 v117, v129, v120, -v130
	v_exp_f32_e32 v120, v117
	v_fma_f32 v117, v129, v121, -v130
	v_add_f32_e32 v116, v131, v116
	v_exp_f32_e32 v121, v117
	v_fma_f32 v117, v129, v122, -v130
	v_add_f32_e32 v116, v133, v116
	v_exp_f32_e32 v122, v117
	v_fma_f32 v117, v129, v123, -v130
	v_add_f32_e32 v116, v119, v116
	v_exp_f32_e32 v123, v117
	v_fma_f32 v117, v129, v124, -v130
	v_add_f32_e32 v116, v120, v116
	v_exp_f32_e32 v124, v117
	v_fma_f32 v117, v129, v125, -v130
	v_add_f32_e32 v116, v121, v116
	v_exp_f32_e32 v125, v117
	v_fma_f32 v117, v129, v126, -v130
	v_add_f32_e32 v116, v122, v116
	v_exp_f32_e32 v126, v117
	v_fma_f32 v117, v129, v127, -v130
	v_add_f32_e32 v116, v123, v116
	v_exp_f32_e32 v127, v117
	v_fma_f32 v96, v129, v96, -v130
	v_add_f32_e32 v116, v124, v116
	v_exp_f32_e32 v96, v96
	v_fma_f32 v97, v129, v97, -v130
	v_add_f32_e32 v116, v125, v116
	v_exp_f32_e32 v97, v97
	v_fma_f32 v98, v129, v98, -v130
	v_add_f32_e32 v116, v126, v116
	v_exp_f32_e32 v98, v98
	v_fma_f32 v99, v129, v99, -v130
	v_add_f32_e32 v134, v127, v116
	v_exp_f32_e32 v99, v99
	v_fma_f32 v100, v129, v100, -v130
	v_cvt_pk_bf16_f32 v116, v112, v113
	v_cvt_pk_bf16_f32 v112, v120, v121
	v_add_f32_e32 v120, v96, v134
	v_exp_f32_e32 v121, v100
	v_add_f32_e32 v120, v97, v120
	v_add_f32_e32 v120, v98, v120
	v_add_f32_e32 v120, v99, v120
	v_fma_f32 v101, v129, v101, -v130
	v_add_f32_e32 v100, v121, v120
	v_exp_f32_e32 v120, v101
	v_fma_f32 v101, v129, v102, -v130
	v_cvt_pk_bf16_f32 v113, v122, v123
	v_exp_f32_e32 v122, v101
	v_fma_f32 v101, v129, v103, -v130
	v_exp_f32_e32 v103, v101
	v_fma_f32 v101, v129, v104, -v130
	v_exp_f32_e32 v104, v101
	v_fma_f32 v101, v129, v105, -v130
	v_add_f32_e32 v100, v120, v100
	v_exp_f32_e32 v105, v101
	v_fma_f32 v101, v129, v106, -v130
	v_add_f32_e32 v100, v122, v100
	v_exp_f32_e32 v106, v101
	v_fma_f32 v101, v129, v107, -v130
	v_add_f32_e32 v100, v103, v100
	v_exp_f32_e32 v107, v101
	v_fma_f32 v101, v129, v108, -v130
	v_add_f32_e32 v100, v104, v100
	v_exp_f32_e32 v108, v101
	v_fma_f32 v101, v129, v109, -v130
	v_add_f32_e32 v100, v105, v100
	v_exp_f32_e32 v109, v101
	v_fma_f32 v101, v129, v110, -v130
	v_add_f32_e32 v100, v106, v100
	v_exp_f32_e32 v110, v101
	v_fma_f32 v101, v129, v111, -v130
	v_add_f32_e32 v100, v107, v100
	v_exp_f32_e32 v111, v101
	v_fma_f32 v80, v129, v80, -v130
	v_add_f32_e32 v100, v108, v100
	v_exp_f32_e32 v80, v80
	v_fma_f32 v81, v129, v81, -v130
	v_add_f32_e32 v100, v109, v100
	v_exp_f32_e32 v81, v81
	v_fma_f32 v82, v129, v82, -v130
	v_add_f32_e32 v100, v110, v100
	v_exp_f32_e32 v82, v82
	v_fma_f32 v83, v129, v83, -v130
	v_add_f32_e32 v123, v111, v100
	v_exp_f32_e32 v83, v83
	v_fma_f32 v84, v129, v84, -v130
	v_cvt_pk_bf16_f32 v100, v96, v97
	v_cvt_pk_bf16_f32 v96, v104, v105
	v_add_f32_e32 v104, v80, v123
	v_exp_f32_e32 v105, v84
	v_add_f32_e32 v104, v81, v104
	v_add_f32_e32 v104, v82, v104
	v_add_f32_e32 v104, v83, v104
	v_fma_f32 v85, v129, v85, -v130
	v_add_f32_e32 v84, v105, v104
	v_exp_f32_e32 v104, v85
	v_fma_f32 v85, v129, v86, -v130
	v_cvt_pk_bf16_f32 v97, v106, v107
	v_exp_f32_e32 v106, v85
	v_fma_f32 v85, v129, v87, -v130
	v_exp_f32_e32 v87, v85
	v_fma_f32 v85, v129, v88, -v130
	v_exp_f32_e32 v88, v85
	v_fma_f32 v85, v129, v89, -v130
	v_add_f32_e32 v84, v104, v84
	v_exp_f32_e32 v89, v85
	v_fma_f32 v85, v129, v90, -v130
	v_add_f32_e32 v84, v106, v84
	v_exp_f32_e32 v90, v85
	v_fma_f32 v85, v129, v91, -v130
	v_add_f32_e32 v84, v87, v84
	v_exp_f32_e32 v91, v85
	v_fma_f32 v85, v129, v92, -v130
	v_add_f32_e32 v84, v88, v84
	v_exp_f32_e32 v92, v85
	v_fma_f32 v85, v129, v93, -v130
	v_add_f32_e32 v84, v89, v84
	v_exp_f32_e32 v93, v85
	v_fma_f32 v85, v129, v94, -v130
	v_add_f32_e32 v84, v90, v84
	v_exp_f32_e32 v94, v85
	v_fma_f32 v85, v129, v95, -v130
	v_add_f32_e32 v84, v91, v84
	v_exp_f32_e32 v95, v85
	v_fma_f32 v64, v129, v64, -v130
	v_add_f32_e32 v84, v92, v84
	v_exp_f32_e32 v64, v64
	v_fma_f32 v65, v129, v65, -v130
	v_add_f32_e32 v84, v93, v84
	v_exp_f32_e32 v65, v65
	v_fma_f32 v66, v129, v66, -v130
	v_add_f32_e32 v84, v94, v84
	v_exp_f32_e32 v66, v66
	v_fma_f32 v67, v129, v67, -v130
	v_add_f32_e32 v107, v95, v84
	v_exp_f32_e32 v67, v67
	v_fma_f32 v68, v129, v68, -v130
	v_cvt_pk_bf16_f32 v84, v80, v81
	v_cvt_pk_bf16_f32 v80, v88, v89
	v_add_f32_e32 v88, v64, v107
	v_exp_f32_e32 v89, v68
	v_add_f32_e32 v88, v65, v88
	v_add_f32_e32 v88, v66, v88
	v_add_f32_e32 v88, v67, v88
	v_fma_f32 v69, v129, v69, -v130
	v_add_f32_e32 v68, v89, v88
	v_exp_f32_e32 v88, v69
	v_fma_f32 v69, v129, v70, -v130
	v_cvt_pk_bf16_f32 v81, v90, v91
	v_exp_f32_e32 v90, v69
	v_fma_f32 v69, v129, v71, -v130
	v_exp_f32_e32 v71, v69
	v_fma_f32 v69, v129, v72, -v130
	v_exp_f32_e32 v72, v69
	v_fma_f32 v69, v129, v73, -v130
	v_add_f32_e32 v68, v88, v68
	v_exp_f32_e32 v73, v69
	v_fma_f32 v69, v129, v74, -v130
	v_add_f32_e32 v68, v90, v68
	v_exp_f32_e32 v74, v69
	v_fma_f32 v69, v129, v75, -v130
	v_add_f32_e32 v68, v71, v68
	v_exp_f32_e32 v75, v69
	v_fma_f32 v69, v129, v76, -v130
	v_add_f32_e32 v68, v72, v68
	v_exp_f32_e32 v76, v69
	v_fma_f32 v69, v129, v77, -v130
	v_add_f32_e32 v68, v73, v68
	v_exp_f32_e32 v77, v69
	v_fma_f32 v69, v129, v78, -v130
	v_add_f32_e32 v68, v74, v68
	v_exp_f32_e32 v78, v69
	v_fma_f32 v69, v129, v79, -v130
	v_add_f32_e32 v68, v75, v68
	v_exp_f32_e32 v79, v69
	v_fma_f32 v48, v129, v48, -v130
	v_add_f32_e32 v68, v76, v68
	v_exp_f32_e32 v48, v48
	v_fma_f32 v49, v129, v49, -v130
	v_add_f32_e32 v68, v77, v68
	v_exp_f32_e32 v49, v49
	v_fma_f32 v50, v129, v50, -v130
	v_add_f32_e32 v68, v78, v68
	v_exp_f32_e32 v50, v50
	v_fma_f32 v51, v129, v51, -v130
	v_add_f32_e32 v91, v79, v68
	v_exp_f32_e32 v51, v51
	v_fma_f32 v52, v129, v52, -v130
	v_cvt_pk_bf16_f32 v68, v64, v65
	v_cvt_pk_bf16_f32 v64, v72, v73
	v_add_f32_e32 v72, v48, v91
	v_exp_f32_e32 v73, v52
	v_add_f32_e32 v72, v49, v72
	v_add_f32_e32 v72, v50, v72
	v_add_f32_e32 v72, v51, v72
	v_fma_f32 v53, v129, v53, -v130
	v_add_f32_e32 v52, v73, v72
	v_exp_f32_e32 v72, v53
	v_fma_f32 v53, v129, v54, -v130
	v_cvt_pk_bf16_f32 v65, v74, v75
	v_exp_f32_e32 v74, v53
	v_fma_f32 v53, v129, v55, -v130
	v_exp_f32_e32 v55, v53
	v_fma_f32 v53, v129, v56, -v130
	v_exp_f32_e32 v56, v53
	v_fma_f32 v53, v129, v57, -v130
	v_add_f32_e32 v52, v72, v52
	v_exp_f32_e32 v57, v53
	v_fma_f32 v53, v129, v58, -v130
	v_add_f32_e32 v52, v74, v52
	v_exp_f32_e32 v58, v53
	v_fma_f32 v53, v129, v59, -v130
	v_add_f32_e32 v52, v55, v52
	v_exp_f32_e32 v59, v53
	v_fma_f32 v53, v129, v60, -v130
	v_add_f32_e32 v52, v56, v52
	v_exp_f32_e32 v60, v53
	v_fma_f32 v53, v129, v61, -v130
	v_add_f32_e32 v52, v57, v52
	v_exp_f32_e32 v61, v53
	v_fma_f32 v53, v129, v62, -v130
	v_add_f32_e32 v52, v58, v52
	v_exp_f32_e32 v62, v53
	v_fma_f32 v53, v129, v63, -v130
	v_add_f32_e32 v52, v59, v52
	v_exp_f32_e32 v63, v53
	v_fma_f32 v32, v129, v32, -v130
	v_add_f32_e32 v52, v60, v52
	v_exp_f32_e32 v32, v32
	v_fma_f32 v33, v129, v33, -v130
	v_add_f32_e32 v52, v61, v52
	v_exp_f32_e32 v33, v33
	v_fma_f32 v34, v129, v34, -v130
	v_add_f32_e32 v52, v62, v52
	v_exp_f32_e32 v34, v34
	v_fma_f32 v35, v129, v35, -v130
	v_add_f32_e32 v75, v63, v52
	v_exp_f32_e32 v35, v35
	v_fma_f32 v36, v129, v36, -v130
	v_cvt_pk_bf16_f32 v52, v48, v49
	v_cvt_pk_bf16_f32 v48, v56, v57
	v_add_f32_e32 v56, v32, v75
	v_exp_f32_e32 v57, v36
	v_add_f32_e32 v56, v33, v56
	v_add_f32_e32 v56, v34, v56
	v_add_f32_e32 v56, v35, v56
	v_fma_f32 v37, v129, v37, -v130
	v_add_f32_e32 v36, v57, v56
	v_exp_f32_e32 v56, v37
	v_fma_f32 v37, v129, v38, -v130
	v_cvt_pk_bf16_f32 v49, v58, v59
	v_exp_f32_e32 v58, v37
	v_fma_f32 v37, v129, v39, -v130
	v_exp_f32_e32 v39, v37
	v_fma_f32 v37, v129, v40, -v130
	v_exp_f32_e32 v40, v37
	v_fma_f32 v37, v129, v41, -v130
	v_add_f32_e32 v36, v56, v36
	v_exp_f32_e32 v41, v37
	v_fma_f32 v37, v129, v42, -v130
	v_add_f32_e32 v36, v58, v36
	v_exp_f32_e32 v42, v37
	v_fma_f32 v37, v129, v43, -v130
	v_add_f32_e32 v36, v39, v36
	v_exp_f32_e32 v43, v37
	v_fma_f32 v37, v129, v44, -v130
	v_add_f32_e32 v36, v40, v36
	v_exp_f32_e32 v44, v37
	v_fma_f32 v37, v129, v45, -v130
	v_add_f32_e32 v36, v41, v36
	v_exp_f32_e32 v45, v37
	v_fma_f32 v37, v129, v46, -v130
	v_add_f32_e32 v36, v42, v36
	v_exp_f32_e32 v46, v37
	v_fma_f32 v37, v129, v47, -v130
	v_add_f32_e32 v36, v43, v36
	v_exp_f32_e32 v47, v37
	v_fma_f32 v16, v129, v16, -v130
	v_add_f32_e32 v36, v44, v36
	v_exp_f32_e32 v16, v16
	v_fma_f32 v17, v129, v17, -v130
	v_add_f32_e32 v36, v45, v36
	v_exp_f32_e32 v17, v17
	v_fma_f32 v18, v129, v18, -v130
	v_add_f32_e32 v36, v46, v36
	v_exp_f32_e32 v18, v18
	v_fma_f32 v19, v129, v19, -v130
	v_add_f32_e32 v59, v47, v36
	v_exp_f32_e32 v19, v19
	v_fma_f32 v20, v129, v20, -v130
	v_cvt_pk_bf16_f32 v36, v32, v33
	v_cvt_pk_bf16_f32 v32, v40, v41
	v_add_f32_e32 v40, v16, v59
	v_exp_f32_e32 v41, v20
	v_add_f32_e32 v40, v17, v40
	v_add_f32_e32 v40, v18, v40
	v_add_f32_e32 v40, v19, v40
	v_fma_f32 v21, v129, v21, -v130
	v_add_f32_e32 v20, v41, v40
	v_exp_f32_e32 v40, v21
	v_fma_f32 v21, v129, v22, -v130
	v_cvt_pk_bf16_f32 v33, v42, v43
	v_exp_f32_e32 v42, v21
	v_fma_f32 v21, v129, v23, -v130
	v_exp_f32_e32 v23, v21
	v_fma_f32 v21, v129, v24, -v130
	v_exp_f32_e32 v24, v21
	v_fma_f32 v21, v129, v25, -v130
	v_add_f32_e32 v20, v40, v20
	v_exp_f32_e32 v25, v21
	v_fma_f32 v21, v129, v26, -v130
	v_add_f32_e32 v20, v42, v20
	v_exp_f32_e32 v26, v21
	v_fma_f32 v21, v129, v27, -v130
	v_add_f32_e32 v20, v23, v20
	v_exp_f32_e32 v27, v21
	v_fma_f32 v21, v129, v28, -v130
	v_add_f32_e32 v20, v24, v20
	v_exp_f32_e32 v28, v21
	v_fma_f32 v21, v129, v29, -v130
	v_add_f32_e32 v20, v25, v20
	v_exp_f32_e32 v29, v21
	v_fma_f32 v21, v129, v30, -v130
	v_add_f32_e32 v20, v26, v20
	v_exp_f32_e32 v30, v21
	v_fma_f32 v21, v129, v31, -v130
	v_add_f32_e32 v20, v27, v20
	v_exp_f32_e32 v31, v21
	v_fma_f32 v0, v129, v0, -v130
	v_add_f32_e32 v20, v28, v20
	v_exp_f32_e32 v0, v0
	v_fma_f32 v1, v129, v1, -v130
	v_add_f32_e32 v20, v29, v20
	v_exp_f32_e32 v1, v1
	v_fma_f32 v2, v129, v2, -v130
	v_add_f32_e32 v20, v30, v20
	v_exp_f32_e32 v2, v2
	v_fma_f32 v3, v129, v3, -v130
	v_add_f32_e32 v43, v31, v20
	v_exp_f32_e32 v3, v3
	v_fma_f32 v4, v129, v4, -v130
	v_cvt_pk_bf16_f32 v20, v16, v17
	v_cvt_pk_bf16_f32 v16, v24, v25
	v_add_f32_e32 v24, v0, v43
	v_exp_f32_e32 v4, v4
	v_fma_f32 v5, v129, v5, -v130
	v_add_f32_e32 v24, v1, v24
	v_exp_f32_e32 v5, v5
	v_fma_f32 v6, v129, v6, -v130
	v_add_f32_e32 v24, v2, v24
	v_exp_f32_e32 v6, v6
	v_fma_f32 v7, v129, v7, -v130
	v_add_f32_e32 v24, v3, v24
	v_exp_f32_e32 v7, v7
	v_fma_f32 v8, v129, v8, -v130
	v_add_f32_e32 v24, v4, v24
	v_exp_f32_e32 v8, v8
	v_fma_f32 v9, v129, v9, -v130
	v_add_f32_e32 v24, v5, v24
	v_exp_f32_e32 v9, v9
	v_fma_f32 v10, v129, v10, -v130
	v_add_f32_e32 v24, v6, v24
	v_exp_f32_e32 v10, v10
	v_fma_f32 v11, v129, v11, -v130
	v_add_f32_e32 v24, v7, v24
	v_exp_f32_e32 v11, v11
	v_fma_f32 v12, v129, v12, -v130
	v_add_f32_e32 v24, v8, v24
	v_exp_f32_e32 v12, v12
	v_fma_f32 v13, v129, v13, -v130
	v_add_f32_e32 v24, v9, v24
	v_exp_f32_e32 v13, v13
	v_fma_f32 v14, v129, v14, -v130
	v_add_f32_e32 v24, v10, v24
	v_exp_f32_e32 v14, v14
	v_fma_f32 v15, v129, v15, -v130
	v_add_f32_e32 v24, v11, v24
	v_exp_f32_e32 v15, v15
	v_add_f32_e32 v24, v12, v24
	v_add_f32_e32 v24, v13, v24
	v_add_f32_e32 v24, v14, v24
	v_cvt_pk_bf16_f32 v22, v41, v40
	v_add_f32_e32 v40, v15, v24
	v_cvt_pk_bf16_f32 v21, v18, v19
	v_cvt_pk_bf16_f32 v18, v28, v29
	v_cvt_pk_bf16_f32 v28, v0, v1
	ds_bpermute_b32 v0, v128, v40
	v_cvt_pk_bf16_f32 v117, v114, v115
	v_cvt_pk_bf16_f32 v118, v132, v131
	v_cvt_pk_bf16_f32 v119, v133, v119
	v_cvt_pk_bf16_f32 v114, v124, v125
	v_cvt_pk_bf16_f32 v115, v126, v127
	v_cvt_pk_bf16_f32 v101, v98, v99
	v_cvt_pk_bf16_f32 v102, v121, v120
	v_cvt_pk_bf16_f32 v103, v122, v103
	v_cvt_pk_bf16_f32 v98, v108, v109
	v_cvt_pk_bf16_f32 v99, v110, v111
	v_cvt_pk_bf16_f32 v85, v82, v83
	v_cvt_pk_bf16_f32 v86, v105, v104
	v_cvt_pk_bf16_f32 v87, v106, v87
	v_cvt_pk_bf16_f32 v82, v92, v93
	v_cvt_pk_bf16_f32 v83, v94, v95
	v_cvt_pk_bf16_f32 v69, v66, v67
	v_cvt_pk_bf16_f32 v70, v89, v88
	v_cvt_pk_bf16_f32 v71, v90, v71
	v_cvt_pk_bf16_f32 v66, v76, v77
	v_cvt_pk_bf16_f32 v67, v78, v79
	v_cvt_pk_bf16_f32 v53, v50, v51
	v_cvt_pk_bf16_f32 v54, v73, v72
	v_cvt_pk_bf16_f32 v55, v74, v55
	v_cvt_pk_bf16_f32 v50, v60, v61
	v_cvt_pk_bf16_f32 v51, v62, v63
	v_cvt_pk_bf16_f32 v37, v34, v35
	v_cvt_pk_bf16_f32 v38, v57, v56
	v_cvt_pk_bf16_f32 v39, v58, v39
	v_cvt_pk_bf16_f32 v34, v44, v45
	v_cvt_pk_bf16_f32 v35, v46, v47
	v_cvt_pk_bf16_f32 v23, v42, v23
	v_cvt_pk_bf16_f32 v17, v26, v27
	v_cvt_pk_bf16_f32 v19, v30, v31
	v_cvt_pk_bf16_f32 v29, v2, v3
	v_cvt_pk_bf16_f32 v30, v4, v5
	v_cvt_pk_bf16_f32 v31, v6, v7
	v_cvt_pk_bf16_f32 v24, v8, v9
	v_cvt_pk_bf16_f32 v25, v10, v11
	v_cvt_pk_bf16_f32 v26, v12, v13
	v_cvt_pk_bf16_f32 v27, v14, v15
	v_lshl_add_u64 v[60:61], v[160:161], 0, s[38:39]
	s_waitcnt lgkmcnt(0)
	v_add_f32_e32 v72, v40, v0
	s_barrier
	s_waitcnt vmcnt(0)
	ds_write_b128 v172, v[228:231]
	ds_write_b128 v172, v[224:227] offset:128
	ds_write_b128 v172, v[216:219] offset:256
	ds_write_b128 v172, v[212:215] offset:384
	ds_write_b128 v172, v[232:235] offset:35840
	ds_write_b128 v172, v[246:249] offset:35968
	ds_write_b128 v172, v[240:243] offset:36096
	ds_write_b128 v172, v[236:239] offset:36224
	v_lshl_add_u64 v[12:13], v[160:161], 0, s[40:41]
	v_lshl_add_u64 v[60:61], v[160:161], 0, s[44:45]
	global_load_dwordx4 v[0:3], v[164:165], off offset:2048
	global_load_dwordx4 v[4:7], v[12:13], off offset:384
	global_load_dwordx4 v[8:11], v[12:13], off offset:256
	s_nop 0
	global_load_dwordx4 v[12:15], v[12:13], off offset:128
	s_nop 0
	global_load_dwordx4 v[40:43], v[166:167], off offset:2048
	global_load_dwordx4 v[44:47], v[60:61], off offset:384
	global_load_dwordx4 v[56:59], v[60:61], off offset:256
	s_nop 0
	global_load_dwordx4 v[60:63], v[60:61], off offset:128
	s_waitcnt vmcnt(7)
	ds_write_b128 v173, v[0:3]
	s_waitcnt vmcnt(4)
	ds_write_b128 v174, v[12:15]
	ds_write_b128 v175, v[8:11]
	ds_write_b128 v179, v[4:7]
	s_waitcnt vmcnt(3)
	ds_write_b128 v182, v[40:43]
	s_waitcnt vmcnt(0)
	ds_write_b128 v183, v[60:63]
	ds_write_b128 v184, v[56:59]
	ds_write_b128 v185, v[44:47]
	v_div_scale_f32 v0, s[4:5], v72, v72, 1.0
	v_rcp_f32_e32 v1, v0
	s_waitcnt lgkmcnt(0)
	s_barrier
	v_fma_f32 v2, -v0, v1, 1.0
	v_fmac_f32_e32 v1, v2, v1
	v_div_scale_f32 v2, vcc, 1.0, v72, 1.0
	v_mul_f32_e32 v3, v2, v1
	v_fma_f32 v4, -v0, v3, v2
	v_fmac_f32_e32 v3, v4, v1
	v_fma_f32 v0, -v0, v3, v2
	v_div_fmas_f32 v0, v0, v1, v3
	v_div_fixup_f32 v44, v0, v72, 1.0
	v_lshl_add_u64 v[0:1], s[12:13], 0, v[162:163]
	v_lshl_add_u64 v[0:1], v[0:1], 0, s[10:11]
	v_lshl_add_u64 v[46:47], v[0:1], 0, v[158:159]
	v_mbcnt_lo_u32_b32 v40, -1, 0
	v_mbcnt_hi_u32_b32 v40, -1, v40
	v_and_b32_e32 v40, 32, v40
	v_lshrrev_b32_e32 v40, 2, v40
	v_mov_b32_e32 v41, 0
	v_lshl_add_u64 v[124:125], v[46:47], 0, v[40:41]
	ds_read_b64_tr_b16 v[56:57], v186
	ds_read_b64_tr_b16 v[58:59], v186 offset:4480
	ds_read_b64_tr_b16 v[60:61], v186 offset:8960
	ds_read_b64_tr_b16 v[62:63], v186 offset:13440
	ds_read_b64_tr_b16 v[88:89], v186 offset:17920
	ds_read_b64_tr_b16 v[90:91], v186 offset:22400
	ds_read_b64_tr_b16 v[92:93], v186 offset:26880
	ds_read_b64_tr_b16 v[94:95], v186 offset:31360
	ds_read_b64_tr_b16 v[104:105], v186 offset:35840
	ds_read_b64_tr_b16 v[106:107], v186 offset:40320
	ds_read_b64_tr_b16 v[108:109], v186 offset:44800
	ds_read_b64_tr_b16 v[110:111], v186 offset:49280
	ds_read_b64_tr_b16 v[120:121], v186 offset:53760
	ds_read_b64_tr_b16 v[122:123], v186 offset:58240
	s_mov_b64 s[4:5], 0
	s_waitcnt lgkmcnt(12)
	v_mfma_f32_32x32x16_bf16 v[0:15], v[56:59], v[116:119], 0
	v_add_u32_e32 v40, v187, v177
	ds_read_b64_tr_b16 v[56:57], v186 offset:62720
	ds_read_b64_tr_b16 v[58:59], v40
	s_waitcnt lgkmcnt(12)
	v_mfma_f32_32x32x16_bf16 v[0:15], v[60:63], v[112:115], v[0:15]
	v_add_u32_e32 v40, v188, v177
	v_add_u32_e32 v42, v189, v177
	ds_read_b64_tr_b16 v[60:61], v40
	ds_read_b64_tr_b16 v[62:63], v42
	s_waitcnt lgkmcnt(12)
	v_mfma_f32_32x32x16_bf16 v[0:15], v[88:91], v[100:103], v[0:15]
	v_add_u32_e32 v40, v190, v177
	v_add_u32_e32 v42, v191, v177
	ds_read_b64_tr_b16 v[88:89], v40
	ds_read_b64_tr_b16 v[90:91], v42
	s_waitcnt lgkmcnt(12)
	v_mfma_f32_32x32x16_bf16 v[0:15], v[92:95], v[96:99], v[0:15]
	v_add_u32_e32 v40, v192, v177
	v_add_u32_e32 v42, v193, v177
	ds_read_b64_tr_b16 v[92:93], v40
	ds_read_b64_tr_b16 v[94:95], v42
	s_waitcnt lgkmcnt(12)
	v_mfma_f32_32x32x16_bf16 v[0:15], v[104:107], v[84:87], v[0:15]
	v_add_u32_e32 v40, v194, v177
	v_add_u32_e32 v42, v195, v177
	ds_read_b64_tr_b16 v[104:105], v40
	ds_read_b64_tr_b16 v[106:107], v42
	s_waitcnt lgkmcnt(12)
	v_mfma_f32_32x32x16_bf16 v[0:15], v[108:111], v[80:83], v[0:15]
	v_add_u32_e32 v40, v196, v177
	v_add_u32_e32 v42, v197, v177
	ds_read_b64_tr_b16 v[108:109], v40
	ds_read_b64_tr_b16 v[110:111], v42
	s_waitcnt lgkmcnt(12)
	v_mfma_f32_32x32x16_bf16 v[0:15], v[120:123], v[68:71], v[0:15]
	v_add_u32_e32 v40, v198, v177
	v_add_u32_e32 v42, v199, v177
	ds_read_b64_tr_b16 v[120:121], v40
	ds_read_b64_tr_b16 v[122:123], v42
	s_waitcnt lgkmcnt(12)
	v_mfma_f32_32x32x16_bf16 v[0:15], v[56:59], v[64:67], v[0:15]
	v_add_u32_e32 v40, v200, v177
	v_add_u32_e32 v42, v201, v177
	ds_read_b64_tr_b16 v[56:57], v40
	ds_read_b64_tr_b16 v[58:59], v42
	s_waitcnt lgkmcnt(12)
	v_mfma_f32_32x32x16_bf16 v[0:15], v[60:63], v[52:55], v[0:15]
	v_add_u32_e32 v40, v202, v177
	v_add_u32_e32 v42, v203, v177
	ds_read_b64_tr_b16 v[60:61], v40
	ds_read_b64_tr_b16 v[62:63], v42
	s_waitcnt lgkmcnt(12)
	v_mfma_f32_32x32x16_bf16 v[0:15], v[88:91], v[48:51], v[0:15]
	ds_read_b64_tr_b16 v[88:89], v186 offset:64
	ds_read_b64_tr_b16 v[90:91], v186 offset:4544
	s_waitcnt lgkmcnt(12)
	v_mfma_f32_32x32x16_bf16 v[0:15], v[92:95], v[36:39], v[0:15]
	ds_read_b64_tr_b16 v[92:93], v186 offset:9024
	ds_read_b64_tr_b16 v[94:95], v186 offset:13504
	s_waitcnt lgkmcnt(12)
	v_mfma_f32_32x32x16_bf16 v[0:15], v[104:107], v[32:35], v[0:15]
	ds_read_b64_tr_b16 v[104:105], v186 offset:17984
	ds_read_b64_tr_b16 v[106:107], v186 offset:22464
	s_waitcnt lgkmcnt(12)
	v_mfma_f32_32x32x16_bf16 v[0:15], v[108:111], v[20:23], v[0:15]
	ds_read_b64_tr_b16 v[108:109], v186 offset:26944
	ds_read_b64_tr_b16 v[110:111], v186 offset:31424
	s_waitcnt lgkmcnt(12)
	v_mfma_f32_32x32x16_bf16 v[0:15], v[120:123], v[16:19], v[0:15]
	ds_read_b64_tr_b16 v[120:121], v186 offset:35904
	ds_read_b64_tr_b16 v[122:123], v186 offset:40384
	s_waitcnt lgkmcnt(12)
	v_mfma_f32_32x32x16_bf16 v[0:15], v[56:59], v[28:31], v[0:15]
	ds_read_b64_tr_b16 v[56:57], v186 offset:44864
	ds_read_b64_tr_b16 v[58:59], v186 offset:49344
	s_waitcnt lgkmcnt(12)
	v_mfma_f32_32x32x16_bf16 v[0:15], v[60:63], v[24:27], v[0:15]
	ds_read_b64_tr_b16 v[60:61], v186 offset:53824
	ds_read_b64_tr_b16 v[62:63], v186 offset:58304
	s_nop 11
	v_pk_mul_f32 v[0:1], v[0:1], v[44:45] op_sel_hi:[1,0]
	v_pk_mul_f32 v[2:3], v[2:3], v[44:45] op_sel_hi:[1,0]
	v_pk_mul_f32 v[4:5], v[4:5], v[44:45] op_sel_hi:[1,0]
	v_pk_mul_f32 v[6:7], v[6:7], v[44:45] op_sel_hi:[1,0]
	v_cvt_pk_bf16_f32 v0, v0, v1
	v_cvt_pk_bf16_f32 v1, v2, v3
	v_cvt_pk_bf16_f32 v2, v4, v5
	v_cvt_pk_bf16_f32 v3, v6, v7
	s_nop 1
	v_permlane32_swap_b32_e32 v0, v2
	v_permlane32_swap_b32_e32 v1, v3
	global_store_dwordx4 v[124:125], v[0:3], off
	v_pk_mul_f32 v[8:9], v[8:9], v[44:45] op_sel_hi:[1,0]
	v_pk_mul_f32 v[10:11], v[10:11], v[44:45] op_sel_hi:[1,0]
	v_pk_mul_f32 v[12:13], v[12:13], v[44:45] op_sel_hi:[1,0]
	v_pk_mul_f32 v[14:15], v[14:15], v[44:45] op_sel_hi:[1,0]
	v_cvt_pk_bf16_f32 v4, v8, v9
	v_cvt_pk_bf16_f32 v5, v10, v11
	v_cvt_pk_bf16_f32 v6, v12, v13
	v_cvt_pk_bf16_f32 v7, v14, v15
	s_nop 1
	v_permlane32_swap_b32_e32 v4, v6
	v_permlane32_swap_b32_e32 v5, v7
	global_store_dwordx4 v[124:125], v[4:7], off offset:32
	s_nop 1
	s_waitcnt lgkmcnt(12)
	v_mfma_f32_32x32x16_bf16 v[0:15], v[88:91], v[116:119], 0
	v_add_u32_e32 v40, v187, v204
	ds_read_b64_tr_b16 v[88:89], v186 offset:62784
	ds_read_b64_tr_b16 v[90:91], v40
	s_waitcnt lgkmcnt(12)
	v_mfma_f32_32x32x16_bf16 v[0:15], v[92:95], v[112:115], v[0:15]
	v_add_u32_e32 v40, v188, v204
	v_add_u32_e32 v42, v189, v204
	ds_read_b64_tr_b16 v[92:93], v40
	ds_read_b64_tr_b16 v[94:95], v42
	s_waitcnt lgkmcnt(12)
	v_mfma_f32_32x32x16_bf16 v[0:15], v[104:107], v[100:103], v[0:15]
	v_add_u32_e32 v40, v190, v204
	v_add_u32_e32 v42, v191, v204
	ds_read_b64_tr_b16 v[104:105], v40
	ds_read_b64_tr_b16 v[106:107], v42
	s_waitcnt lgkmcnt(12)
	v_mfma_f32_32x32x16_bf16 v[0:15], v[108:111], v[96:99], v[0:15]
	v_add_u32_e32 v40, v192, v204
	v_add_u32_e32 v42, v193, v204
	ds_read_b64_tr_b16 v[108:109], v40
	ds_read_b64_tr_b16 v[110:111], v42
	s_waitcnt lgkmcnt(12)
	v_mfma_f32_32x32x16_bf16 v[0:15], v[120:123], v[84:87], v[0:15]
	v_add_u32_e32 v40, v194, v204
	v_add_u32_e32 v42, v195, v204
	ds_read_b64_tr_b16 v[120:121], v40
	ds_read_b64_tr_b16 v[122:123], v42
	s_waitcnt lgkmcnt(12)
	v_mfma_f32_32x32x16_bf16 v[0:15], v[56:59], v[80:83], v[0:15]
	v_add_u32_e32 v40, v196, v204
	v_add_u32_e32 v42, v197, v204
	ds_read_b64_tr_b16 v[56:57], v40
	ds_read_b64_tr_b16 v[58:59], v42
	s_waitcnt lgkmcnt(12)
	v_mfma_f32_32x32x16_bf16 v[0:15], v[60:63], v[68:71], v[0:15]
	v_add_u32_e32 v40, v198, v204
	v_add_u32_e32 v42, v199, v204
	ds_read_b64_tr_b16 v[60:61], v40
	ds_read_b64_tr_b16 v[62:63], v42
	s_waitcnt lgkmcnt(12)
	v_mfma_f32_32x32x16_bf16 v[0:15], v[88:91], v[64:67], v[0:15]
	v_add_u32_e32 v40, v200, v204
	v_add_u32_e32 v42, v201, v204
	ds_read_b64_tr_b16 v[88:89], v40
	ds_read_b64_tr_b16 v[90:91], v42
	s_waitcnt lgkmcnt(12)
	v_mfma_f32_32x32x16_bf16 v[0:15], v[92:95], v[52:55], v[0:15]
	v_add_u32_e32 v40, v202, v204
	v_add_u32_e32 v42, v203, v204
	ds_read_b64_tr_b16 v[92:93], v40
	ds_read_b64_tr_b16 v[94:95], v42
	s_waitcnt lgkmcnt(12)
	v_mfma_f32_32x32x16_bf16 v[0:15], v[104:107], v[48:51], v[0:15]
	ds_read_b64_tr_b16 v[104:105], v186 offset:128
	ds_read_b64_tr_b16 v[106:107], v186 offset:4608
	s_waitcnt lgkmcnt(12)
	v_mfma_f32_32x32x16_bf16 v[0:15], v[108:111], v[36:39], v[0:15]
	ds_read_b64_tr_b16 v[108:109], v186 offset:9088
	ds_read_b64_tr_b16 v[110:111], v186 offset:13568
	s_waitcnt lgkmcnt(12)
	v_mfma_f32_32x32x16_bf16 v[0:15], v[120:123], v[32:35], v[0:15]
	ds_read_b64_tr_b16 v[120:121], v186 offset:18048
	ds_read_b64_tr_b16 v[122:123], v186 offset:22528
	s_waitcnt lgkmcnt(12)
	v_mfma_f32_32x32x16_bf16 v[0:15], v[56:59], v[20:23], v[0:15]
	ds_read_b64_tr_b16 v[56:57], v186 offset:27008
	ds_read_b64_tr_b16 v[58:59], v186 offset:31488
	s_waitcnt lgkmcnt(12)
	v_mfma_f32_32x32x16_bf16 v[0:15], v[60:63], v[16:19], v[0:15]
	ds_read_b64_tr_b16 v[60:61], v186 offset:35968
	ds_read_b64_tr_b16 v[62:63], v186 offset:40448
	s_waitcnt lgkmcnt(12)
	v_mfma_f32_32x32x16_bf16 v[0:15], v[88:91], v[28:31], v[0:15]
	ds_read_b64_tr_b16 v[88:89], v186 offset:44928
	ds_read_b64_tr_b16 v[90:91], v186 offset:49408
	s_waitcnt lgkmcnt(12)
	v_mfma_f32_32x32x16_bf16 v[0:15], v[92:95], v[24:27], v[0:15]
	ds_read_b64_tr_b16 v[92:93], v186 offset:53888
	ds_read_b64_tr_b16 v[94:95], v186 offset:58368
	s_nop 11
	v_pk_mul_f32 v[0:1], v[0:1], v[44:45] op_sel_hi:[1,0]
	v_pk_mul_f32 v[2:3], v[2:3], v[44:45] op_sel_hi:[1,0]
	v_pk_mul_f32 v[4:5], v[4:5], v[44:45] op_sel_hi:[1,0]
	v_pk_mul_f32 v[6:7], v[6:7], v[44:45] op_sel_hi:[1,0]
	v_cvt_pk_bf16_f32 v0, v0, v1
	v_cvt_pk_bf16_f32 v1, v2, v3
	v_cvt_pk_bf16_f32 v2, v4, v5
	v_cvt_pk_bf16_f32 v3, v6, v7
	s_nop 1
	v_permlane32_swap_b32_e32 v0, v2
	v_permlane32_swap_b32_e32 v1, v3
	global_store_dwordx4 v[124:125], v[0:3], off offset:64
	v_pk_mul_f32 v[8:9], v[8:9], v[44:45] op_sel_hi:[1,0]
	v_pk_mul_f32 v[10:11], v[10:11], v[44:45] op_sel_hi:[1,0]
	v_pk_mul_f32 v[12:13], v[12:13], v[44:45] op_sel_hi:[1,0]
	v_pk_mul_f32 v[14:15], v[14:15], v[44:45] op_sel_hi:[1,0]
	v_cvt_pk_bf16_f32 v4, v8, v9
	v_cvt_pk_bf16_f32 v5, v10, v11
	v_cvt_pk_bf16_f32 v6, v12, v13
	v_cvt_pk_bf16_f32 v7, v14, v15
	s_nop 1
	v_permlane32_swap_b32_e32 v4, v6
	v_permlane32_swap_b32_e32 v5, v7
	global_store_dwordx4 v[124:125], v[4:7], off offset:96
	s_nop 1
	s_waitcnt lgkmcnt(12)
	v_mfma_f32_32x32x16_bf16 v[0:15], v[104:107], v[116:119], 0
	v_add_u32_e32 v40, v187, v205
	ds_read_b64_tr_b16 v[104:105], v186 offset:62848
	ds_read_b64_tr_b16 v[106:107], v40
	s_waitcnt lgkmcnt(12)
	v_mfma_f32_32x32x16_bf16 v[0:15], v[108:111], v[112:115], v[0:15]
	v_add_u32_e32 v40, v188, v205
	v_add_u32_e32 v42, v189, v205
	ds_read_b64_tr_b16 v[108:109], v40
	ds_read_b64_tr_b16 v[110:111], v42
	s_waitcnt lgkmcnt(12)
	v_mfma_f32_32x32x16_bf16 v[0:15], v[120:123], v[100:103], v[0:15]
	v_add_u32_e32 v40, v190, v205
	v_add_u32_e32 v42, v191, v205
	ds_read_b64_tr_b16 v[120:121], v40
	ds_read_b64_tr_b16 v[122:123], v42
	s_waitcnt lgkmcnt(12)
	v_mfma_f32_32x32x16_bf16 v[0:15], v[56:59], v[96:99], v[0:15]
	v_add_u32_e32 v40, v192, v205
	v_add_u32_e32 v42, v193, v205
	ds_read_b64_tr_b16 v[56:57], v40
	ds_read_b64_tr_b16 v[58:59], v42
	s_waitcnt lgkmcnt(12)
	v_mfma_f32_32x32x16_bf16 v[0:15], v[60:63], v[84:87], v[0:15]
	v_add_u32_e32 v40, v194, v205
	v_add_u32_e32 v42, v195, v205
	ds_read_b64_tr_b16 v[60:61], v40
	ds_read_b64_tr_b16 v[62:63], v42
	s_waitcnt lgkmcnt(12)
	v_mfma_f32_32x32x16_bf16 v[0:15], v[88:91], v[80:83], v[0:15]
	v_add_u32_e32 v40, v196, v205
	v_add_u32_e32 v42, v197, v205
	ds_read_b64_tr_b16 v[88:89], v40
	ds_read_b64_tr_b16 v[90:91], v42
	s_waitcnt lgkmcnt(12)
	v_mfma_f32_32x32x16_bf16 v[0:15], v[92:95], v[68:71], v[0:15]
	v_add_u32_e32 v40, v198, v205
	v_add_u32_e32 v42, v199, v205
	ds_read_b64_tr_b16 v[92:93], v40
	ds_read_b64_tr_b16 v[94:95], v42
	s_waitcnt lgkmcnt(12)
	v_mfma_f32_32x32x16_bf16 v[0:15], v[104:107], v[64:67], v[0:15]
	v_add_u32_e32 v40, v200, v205
	v_add_u32_e32 v42, v201, v205
	ds_read_b64_tr_b16 v[104:105], v40
	ds_read_b64_tr_b16 v[106:107], v42
	s_waitcnt lgkmcnt(12)
	v_mfma_f32_32x32x16_bf16 v[0:15], v[108:111], v[52:55], v[0:15]
	v_add_u32_e32 v40, v202, v205
	v_add_u32_e32 v42, v203, v205
	ds_read_b64_tr_b16 v[108:109], v40
	ds_read_b64_tr_b16 v[110:111], v42
	s_waitcnt lgkmcnt(12)
	v_mfma_f32_32x32x16_bf16 v[0:15], v[120:123], v[48:51], v[0:15]
	ds_read_b64_tr_b16 v[120:121], v186 offset:192
	ds_read_b64_tr_b16 v[122:123], v186 offset:4672
	s_waitcnt lgkmcnt(12)
	v_mfma_f32_32x32x16_bf16 v[0:15], v[56:59], v[36:39], v[0:15]
	ds_read_b64_tr_b16 v[56:57], v186 offset:9152
	ds_read_b64_tr_b16 v[58:59], v186 offset:13632
	s_waitcnt lgkmcnt(12)
	v_mfma_f32_32x32x16_bf16 v[0:15], v[60:63], v[32:35], v[0:15]
	ds_read_b64_tr_b16 v[60:61], v186 offset:18112
	ds_read_b64_tr_b16 v[62:63], v186 offset:22592
	s_waitcnt lgkmcnt(12)
	v_mfma_f32_32x32x16_bf16 v[0:15], v[88:91], v[20:23], v[0:15]
	ds_read_b64_tr_b16 v[88:89], v186 offset:27072
	ds_read_b64_tr_b16 v[90:91], v186 offset:31552
	s_waitcnt lgkmcnt(12)
	v_mfma_f32_32x32x16_bf16 v[0:15], v[92:95], v[16:19], v[0:15]
	ds_read_b64_tr_b16 v[92:93], v186 offset:36032
	ds_read_b64_tr_b16 v[94:95], v186 offset:40512
	s_waitcnt lgkmcnt(12)
	v_mfma_f32_32x32x16_bf16 v[0:15], v[104:107], v[28:31], v[0:15]
	ds_read_b64_tr_b16 v[104:105], v186 offset:44992
	ds_read_b64_tr_b16 v[106:107], v186 offset:49472
	s_waitcnt lgkmcnt(12)
	v_mfma_f32_32x32x16_bf16 v[0:15], v[108:111], v[24:27], v[0:15]
	ds_read_b64_tr_b16 v[108:109], v186 offset:53952
	ds_read_b64_tr_b16 v[110:111], v186 offset:58432
	s_nop 11
	v_pk_mul_f32 v[0:1], v[0:1], v[44:45] op_sel_hi:[1,0]
	v_pk_mul_f32 v[2:3], v[2:3], v[44:45] op_sel_hi:[1,0]
	v_pk_mul_f32 v[4:5], v[4:5], v[44:45] op_sel_hi:[1,0]
	v_pk_mul_f32 v[6:7], v[6:7], v[44:45] op_sel_hi:[1,0]
	v_cvt_pk_bf16_f32 v0, v0, v1
	v_cvt_pk_bf16_f32 v1, v2, v3
	v_cvt_pk_bf16_f32 v2, v4, v5
	v_cvt_pk_bf16_f32 v3, v6, v7
	s_nop 1
	v_permlane32_swap_b32_e32 v0, v2
	v_permlane32_swap_b32_e32 v1, v3
	global_store_dwordx4 v[124:125], v[0:3], off offset:128
	v_pk_mul_f32 v[8:9], v[8:9], v[44:45] op_sel_hi:[1,0]
	v_pk_mul_f32 v[10:11], v[10:11], v[44:45] op_sel_hi:[1,0]
	v_pk_mul_f32 v[12:13], v[12:13], v[44:45] op_sel_hi:[1,0]
	v_pk_mul_f32 v[14:15], v[14:15], v[44:45] op_sel_hi:[1,0]
	v_cvt_pk_bf16_f32 v4, v8, v9
	v_cvt_pk_bf16_f32 v5, v10, v11
	v_cvt_pk_bf16_f32 v6, v12, v13
	v_cvt_pk_bf16_f32 v7, v14, v15
	s_nop 1
	v_permlane32_swap_b32_e32 v4, v6
	v_permlane32_swap_b32_e32 v5, v7
	global_store_dwordx4 v[124:125], v[4:7], off offset:160
	s_nop 1
	s_waitcnt lgkmcnt(12)
	v_mfma_f32_32x32x16_bf16 v[0:15], v[120:123], v[116:119], 0
	v_add_u32_e32 v40, v187, v206
	ds_read_b64_tr_b16 v[120:121], v186 offset:62912
	ds_read_b64_tr_b16 v[122:123], v40
	s_waitcnt lgkmcnt(12)
	v_mfma_f32_32x32x16_bf16 v[0:15], v[56:59], v[112:115], v[0:15]
	v_add_u32_e32 v40, v188, v206
	v_add_u32_e32 v42, v189, v206
	ds_read_b64_tr_b16 v[56:57], v40
	ds_read_b64_tr_b16 v[58:59], v42
	s_waitcnt lgkmcnt(12)
	v_mfma_f32_32x32x16_bf16 v[0:15], v[60:63], v[100:103], v[0:15]
	v_add_u32_e32 v40, v190, v206
	v_add_u32_e32 v42, v191, v206
	ds_read_b64_tr_b16 v[60:61], v40
	ds_read_b64_tr_b16 v[62:63], v42
	s_waitcnt lgkmcnt(12)
	v_mfma_f32_32x32x16_bf16 v[0:15], v[88:91], v[96:99], v[0:15]
	v_add_u32_e32 v40, v192, v206
	v_add_u32_e32 v42, v193, v206
	ds_read_b64_tr_b16 v[88:89], v40
	ds_read_b64_tr_b16 v[90:91], v42
	s_waitcnt lgkmcnt(12)
	v_mfma_f32_32x32x16_bf16 v[0:15], v[92:95], v[84:87], v[0:15]
	v_add_u32_e32 v40, v194, v206
	v_add_u32_e32 v42, v195, v206
	ds_read_b64_tr_b16 v[92:93], v40
	ds_read_b64_tr_b16 v[94:95], v42
	s_waitcnt lgkmcnt(12)
	v_mfma_f32_32x32x16_bf16 v[0:15], v[104:107], v[80:83], v[0:15]
	v_add_u32_e32 v40, v196, v206
	v_add_u32_e32 v42, v197, v206
	ds_read_b64_tr_b16 v[104:105], v40
	ds_read_b64_tr_b16 v[106:107], v42
	s_waitcnt lgkmcnt(12)
	v_mfma_f32_32x32x16_bf16 v[0:15], v[108:111], v[68:71], v[0:15]
	v_add_u32_e32 v40, v198, v206
	v_add_u32_e32 v42, v199, v206
	ds_read_b64_tr_b16 v[108:109], v40
	ds_read_b64_tr_b16 v[110:111], v42
	s_waitcnt lgkmcnt(12)
	v_mfma_f32_32x32x16_bf16 v[0:15], v[120:123], v[64:67], v[0:15]
	v_add_u32_e32 v40, v200, v206
	v_add_u32_e32 v42, v201, v206
	ds_read_b64_tr_b16 v[120:121], v40
	ds_read_b64_tr_b16 v[122:123], v42
	s_waitcnt lgkmcnt(12)
	v_mfma_f32_32x32x16_bf16 v[0:15], v[56:59], v[52:55], v[0:15]
	v_add_u32_e32 v40, v202, v206
	v_add_u32_e32 v42, v203, v206
	ds_read_b64_tr_b16 v[56:57], v40
	ds_read_b64_tr_b16 v[58:59], v42
	s_waitcnt lgkmcnt(12)
	v_mfma_f32_32x32x16_bf16 v[0:15], v[60:63], v[48:51], v[0:15]
	ds_read_b64_tr_b16 v[60:61], v186 offset:256
	ds_read_b64_tr_b16 v[62:63], v186 offset:4736
	s_waitcnt lgkmcnt(12)
	v_mfma_f32_32x32x16_bf16 v[0:15], v[88:91], v[36:39], v[0:15]
	ds_read_b64_tr_b16 v[88:89], v186 offset:9216
	ds_read_b64_tr_b16 v[90:91], v186 offset:13696
	s_waitcnt lgkmcnt(12)
	v_mfma_f32_32x32x16_bf16 v[0:15], v[92:95], v[32:35], v[0:15]
	ds_read_b64_tr_b16 v[92:93], v186 offset:18176
	ds_read_b64_tr_b16 v[94:95], v186 offset:22656
	s_waitcnt lgkmcnt(12)
	v_mfma_f32_32x32x16_bf16 v[0:15], v[104:107], v[20:23], v[0:15]
	ds_read_b64_tr_b16 v[104:105], v186 offset:27136
	ds_read_b64_tr_b16 v[106:107], v186 offset:31616
	s_waitcnt lgkmcnt(12)
	v_mfma_f32_32x32x16_bf16 v[0:15], v[108:111], v[16:19], v[0:15]
	ds_read_b64_tr_b16 v[108:109], v186 offset:36096
	ds_read_b64_tr_b16 v[110:111], v186 offset:40576
	s_waitcnt lgkmcnt(12)
	v_mfma_f32_32x32x16_bf16 v[0:15], v[120:123], v[28:31], v[0:15]
	ds_read_b64_tr_b16 v[120:121], v186 offset:45056
	ds_read_b64_tr_b16 v[122:123], v186 offset:49536
	s_waitcnt lgkmcnt(12)
	v_mfma_f32_32x32x16_bf16 v[0:15], v[56:59], v[24:27], v[0:15]
	ds_read_b64_tr_b16 v[56:57], v186 offset:54016
	ds_read_b64_tr_b16 v[58:59], v186 offset:58496
	s_nop 11
	v_pk_mul_f32 v[0:1], v[0:1], v[44:45] op_sel_hi:[1,0]
	v_pk_mul_f32 v[2:3], v[2:3], v[44:45] op_sel_hi:[1,0]
	v_pk_mul_f32 v[4:5], v[4:5], v[44:45] op_sel_hi:[1,0]
	v_pk_mul_f32 v[6:7], v[6:7], v[44:45] op_sel_hi:[1,0]
	v_cvt_pk_bf16_f32 v0, v0, v1
	v_cvt_pk_bf16_f32 v1, v2, v3
	v_cvt_pk_bf16_f32 v2, v4, v5
	v_cvt_pk_bf16_f32 v3, v6, v7
	s_nop 1
	v_permlane32_swap_b32_e32 v0, v2
	v_permlane32_swap_b32_e32 v1, v3
	global_store_dwordx4 v[124:125], v[0:3], off offset:192
	v_pk_mul_f32 v[8:9], v[8:9], v[44:45] op_sel_hi:[1,0]
	v_pk_mul_f32 v[10:11], v[10:11], v[44:45] op_sel_hi:[1,0]
	v_pk_mul_f32 v[12:13], v[12:13], v[44:45] op_sel_hi:[1,0]
	v_pk_mul_f32 v[14:15], v[14:15], v[44:45] op_sel_hi:[1,0]
	v_cvt_pk_bf16_f32 v4, v8, v9
	v_cvt_pk_bf16_f32 v5, v10, v11
	v_cvt_pk_bf16_f32 v6, v12, v13
	v_cvt_pk_bf16_f32 v7, v14, v15
	s_nop 1
	v_permlane32_swap_b32_e32 v4, v6
	v_permlane32_swap_b32_e32 v5, v7
	global_store_dwordx4 v[124:125], v[4:7], off offset:224
	s_nop 1
	s_waitcnt lgkmcnt(12)
	v_mfma_f32_32x32x16_bf16 v[0:15], v[60:63], v[116:119], 0
	v_add_u32_e32 v40, v187, v207
	ds_read_b64_tr_b16 v[60:61], v186 offset:62976
	ds_read_b64_tr_b16 v[62:63], v40
	s_waitcnt lgkmcnt(12)
	v_mfma_f32_32x32x16_bf16 v[0:15], v[88:91], v[112:115], v[0:15]
	v_add_u32_e32 v40, v188, v207
	v_add_u32_e32 v42, v189, v207
	ds_read_b64_tr_b16 v[88:89], v40
	ds_read_b64_tr_b16 v[90:91], v42
	s_waitcnt lgkmcnt(12)
	v_mfma_f32_32x32x16_bf16 v[0:15], v[92:95], v[100:103], v[0:15]
	v_add_u32_e32 v40, v190, v207
	v_add_u32_e32 v42, v191, v207
	ds_read_b64_tr_b16 v[92:93], v40
	ds_read_b64_tr_b16 v[94:95], v42
	s_waitcnt lgkmcnt(12)
	v_mfma_f32_32x32x16_bf16 v[0:15], v[104:107], v[96:99], v[0:15]
	v_add_u32_e32 v40, v192, v207
	v_add_u32_e32 v42, v193, v207
	ds_read_b64_tr_b16 v[104:105], v40
	ds_read_b64_tr_b16 v[106:107], v42
	s_waitcnt lgkmcnt(12)
	v_mfma_f32_32x32x16_bf16 v[0:15], v[108:111], v[84:87], v[0:15]
	v_add_u32_e32 v40, v194, v207
	v_add_u32_e32 v42, v195, v207
	ds_read_b64_tr_b16 v[108:109], v40
	ds_read_b64_tr_b16 v[110:111], v42
	s_waitcnt lgkmcnt(12)
	v_mfma_f32_32x32x16_bf16 v[0:15], v[120:123], v[80:83], v[0:15]
	v_add_u32_e32 v40, v196, v207
	v_add_u32_e32 v42, v197, v207
	ds_read_b64_tr_b16 v[120:121], v40
	ds_read_b64_tr_b16 v[122:123], v42
	s_waitcnt lgkmcnt(12)
	v_mfma_f32_32x32x16_bf16 v[0:15], v[56:59], v[68:71], v[0:15]
	v_add_u32_e32 v40, v198, v207
	v_add_u32_e32 v42, v199, v207
	ds_read_b64_tr_b16 v[56:57], v40
	ds_read_b64_tr_b16 v[58:59], v42
	s_waitcnt lgkmcnt(12)
	v_mfma_f32_32x32x16_bf16 v[0:15], v[60:63], v[64:67], v[0:15]
	v_add_u32_e32 v40, v200, v207
	v_add_u32_e32 v42, v201, v207
	ds_read_b64_tr_b16 v[60:61], v40
	ds_read_b64_tr_b16 v[62:63], v42
	s_waitcnt lgkmcnt(12)
	v_mfma_f32_32x32x16_bf16 v[0:15], v[88:91], v[52:55], v[0:15]
	v_add_u32_e32 v40, v202, v207
	v_add_u32_e32 v42, v203, v207
	ds_read_b64_tr_b16 v[88:89], v40
	ds_read_b64_tr_b16 v[90:91], v42
	s_waitcnt lgkmcnt(12)
	v_mfma_f32_32x32x16_bf16 v[0:15], v[92:95], v[48:51], v[0:15]
	ds_read_b64_tr_b16 v[92:93], v186 offset:320
	ds_read_b64_tr_b16 v[94:95], v186 offset:4800
	s_waitcnt lgkmcnt(12)
	v_mfma_f32_32x32x16_bf16 v[0:15], v[104:107], v[36:39], v[0:15]
	ds_read_b64_tr_b16 v[104:105], v186 offset:9280
	ds_read_b64_tr_b16 v[106:107], v186 offset:13760
	s_waitcnt lgkmcnt(12)
	v_mfma_f32_32x32x16_bf16 v[0:15], v[108:111], v[32:35], v[0:15]
	ds_read_b64_tr_b16 v[108:109], v186 offset:18240
	ds_read_b64_tr_b16 v[110:111], v186 offset:22720
	s_waitcnt lgkmcnt(12)
	v_mfma_f32_32x32x16_bf16 v[0:15], v[120:123], v[20:23], v[0:15]
	ds_read_b64_tr_b16 v[120:121], v186 offset:27200
	ds_read_b64_tr_b16 v[122:123], v186 offset:31680
	s_waitcnt lgkmcnt(12)
	v_mfma_f32_32x32x16_bf16 v[0:15], v[56:59], v[16:19], v[0:15]
	ds_read_b64_tr_b16 v[56:57], v186 offset:36160
	ds_read_b64_tr_b16 v[58:59], v186 offset:40640
	s_waitcnt lgkmcnt(12)
	v_mfma_f32_32x32x16_bf16 v[0:15], v[60:63], v[28:31], v[0:15]
	ds_read_b64_tr_b16 v[60:61], v186 offset:45120
	ds_read_b64_tr_b16 v[62:63], v186 offset:49600
	s_waitcnt lgkmcnt(12)
	v_mfma_f32_32x32x16_bf16 v[0:15], v[88:91], v[24:27], v[0:15]
	ds_read_b64_tr_b16 v[88:89], v186 offset:54080
	ds_read_b64_tr_b16 v[90:91], v186 offset:58560
	s_nop 11
	v_pk_mul_f32 v[0:1], v[0:1], v[44:45] op_sel_hi:[1,0]
	v_pk_mul_f32 v[2:3], v[2:3], v[44:45] op_sel_hi:[1,0]
	v_pk_mul_f32 v[4:5], v[4:5], v[44:45] op_sel_hi:[1,0]
	v_pk_mul_f32 v[6:7], v[6:7], v[44:45] op_sel_hi:[1,0]
	v_cvt_pk_bf16_f32 v0, v0, v1
	v_cvt_pk_bf16_f32 v1, v2, v3
	v_cvt_pk_bf16_f32 v2, v4, v5
	v_cvt_pk_bf16_f32 v3, v6, v7
	s_nop 1
	v_permlane32_swap_b32_e32 v0, v2
	v_permlane32_swap_b32_e32 v1, v3
	global_store_dwordx4 v[124:125], v[0:3], off offset:256
	v_pk_mul_f32 v[8:9], v[8:9], v[44:45] op_sel_hi:[1,0]
	v_pk_mul_f32 v[10:11], v[10:11], v[44:45] op_sel_hi:[1,0]
	v_pk_mul_f32 v[12:13], v[12:13], v[44:45] op_sel_hi:[1,0]
	v_pk_mul_f32 v[14:15], v[14:15], v[44:45] op_sel_hi:[1,0]
	v_cvt_pk_bf16_f32 v4, v8, v9
	v_cvt_pk_bf16_f32 v5, v10, v11
	v_cvt_pk_bf16_f32 v6, v12, v13
	v_cvt_pk_bf16_f32 v7, v14, v15
	s_nop 1
	v_permlane32_swap_b32_e32 v4, v6
	v_permlane32_swap_b32_e32 v5, v7
	global_store_dwordx4 v[124:125], v[4:7], off offset:288
	s_nop 1
	s_waitcnt lgkmcnt(12)
	v_mfma_f32_32x32x16_bf16 v[0:15], v[92:95], v[116:119], 0
	v_add_u32_e32 v40, v187, v208
	ds_read_b64_tr_b16 v[92:93], v186 offset:63040
	ds_read_b64_tr_b16 v[94:95], v40
	s_waitcnt lgkmcnt(12)
	v_mfma_f32_32x32x16_bf16 v[0:15], v[104:107], v[112:115], v[0:15]
	v_add_u32_e32 v40, v188, v208
	v_add_u32_e32 v42, v189, v208
	ds_read_b64_tr_b16 v[104:105], v40
	ds_read_b64_tr_b16 v[106:107], v42
	s_waitcnt lgkmcnt(12)
	v_mfma_f32_32x32x16_bf16 v[0:15], v[108:111], v[100:103], v[0:15]
	v_add_u32_e32 v40, v190, v208
	v_add_u32_e32 v42, v191, v208
	ds_read_b64_tr_b16 v[108:109], v40
	ds_read_b64_tr_b16 v[110:111], v42
	s_waitcnt lgkmcnt(12)
	v_mfma_f32_32x32x16_bf16 v[0:15], v[120:123], v[96:99], v[0:15]
	v_add_u32_e32 v40, v192, v208
	v_add_u32_e32 v42, v193, v208
	ds_read_b64_tr_b16 v[120:121], v40
	ds_read_b64_tr_b16 v[122:123], v42
	s_waitcnt lgkmcnt(12)
	v_mfma_f32_32x32x16_bf16 v[0:15], v[56:59], v[84:87], v[0:15]
	v_add_u32_e32 v40, v194, v208
	v_add_u32_e32 v42, v195, v208
	ds_read_b64_tr_b16 v[56:57], v40
	ds_read_b64_tr_b16 v[58:59], v42
	s_waitcnt lgkmcnt(12)
	v_mfma_f32_32x32x16_bf16 v[0:15], v[60:63], v[80:83], v[0:15]
	v_add_u32_e32 v40, v196, v208
	v_add_u32_e32 v42, v197, v208
	ds_read_b64_tr_b16 v[60:61], v40
	ds_read_b64_tr_b16 v[62:63], v42
	s_waitcnt lgkmcnt(12)
	v_mfma_f32_32x32x16_bf16 v[0:15], v[88:91], v[68:71], v[0:15]
	v_add_u32_e32 v40, v198, v208
	v_add_u32_e32 v42, v199, v208
	ds_read_b64_tr_b16 v[88:89], v40
	ds_read_b64_tr_b16 v[90:91], v42
	s_waitcnt lgkmcnt(12)
	v_mfma_f32_32x32x16_bf16 v[0:15], v[92:95], v[64:67], v[0:15]
	v_add_u32_e32 v40, v200, v208
	v_add_u32_e32 v42, v201, v208
	ds_read_b64_tr_b16 v[92:93], v40
	ds_read_b64_tr_b16 v[94:95], v42
	s_waitcnt lgkmcnt(12)
	v_mfma_f32_32x32x16_bf16 v[0:15], v[104:107], v[52:55], v[0:15]
	v_add_u32_e32 v40, v202, v208
	v_add_u32_e32 v42, v203, v208
	ds_read_b64_tr_b16 v[104:105], v40
	ds_read_b64_tr_b16 v[106:107], v42
	s_waitcnt lgkmcnt(12)
	v_mfma_f32_32x32x16_bf16 v[0:15], v[108:111], v[48:51], v[0:15]
	ds_read_b64_tr_b16 v[108:109], v186 offset:384
	ds_read_b64_tr_b16 v[110:111], v186 offset:4864
	s_waitcnt lgkmcnt(12)
	v_mfma_f32_32x32x16_bf16 v[0:15], v[120:123], v[36:39], v[0:15]
	ds_read_b64_tr_b16 v[120:121], v186 offset:9344
	ds_read_b64_tr_b16 v[122:123], v186 offset:13824
	s_waitcnt lgkmcnt(12)
	v_mfma_f32_32x32x16_bf16 v[0:15], v[56:59], v[32:35], v[0:15]
	ds_read_b64_tr_b16 v[56:57], v186 offset:18304
	ds_read_b64_tr_b16 v[58:59], v186 offset:22784
	s_waitcnt lgkmcnt(12)
	v_mfma_f32_32x32x16_bf16 v[0:15], v[60:63], v[20:23], v[0:15]
	ds_read_b64_tr_b16 v[60:61], v186 offset:27264
	ds_read_b64_tr_b16 v[62:63], v186 offset:31744
	s_waitcnt lgkmcnt(12)
	v_mfma_f32_32x32x16_bf16 v[0:15], v[88:91], v[16:19], v[0:15]
	ds_read_b64_tr_b16 v[88:89], v186 offset:36224
	ds_read_b64_tr_b16 v[90:91], v186 offset:40704
	s_waitcnt lgkmcnt(12)
	v_mfma_f32_32x32x16_bf16 v[0:15], v[92:95], v[28:31], v[0:15]
	ds_read_b64_tr_b16 v[92:93], v186 offset:45184
	ds_read_b64_tr_b16 v[94:95], v186 offset:49664
	s_waitcnt lgkmcnt(12)
	v_mfma_f32_32x32x16_bf16 v[0:15], v[104:107], v[24:27], v[0:15]
	ds_read_b64_tr_b16 v[104:105], v186 offset:54144
	ds_read_b64_tr_b16 v[106:107], v186 offset:58624
	s_nop 11
	v_pk_mul_f32 v[0:1], v[0:1], v[44:45] op_sel_hi:[1,0]
	v_pk_mul_f32 v[2:3], v[2:3], v[44:45] op_sel_hi:[1,0]
	v_pk_mul_f32 v[4:5], v[4:5], v[44:45] op_sel_hi:[1,0]
	v_pk_mul_f32 v[6:7], v[6:7], v[44:45] op_sel_hi:[1,0]
	v_cvt_pk_bf16_f32 v0, v0, v1
	v_cvt_pk_bf16_f32 v1, v2, v3
	v_cvt_pk_bf16_f32 v2, v4, v5
	v_cvt_pk_bf16_f32 v3, v6, v7
	s_nop 1
	v_permlane32_swap_b32_e32 v0, v2
	v_permlane32_swap_b32_e32 v1, v3
	global_store_dwordx4 v[124:125], v[0:3], off offset:320
	v_pk_mul_f32 v[8:9], v[8:9], v[44:45] op_sel_hi:[1,0]
	v_pk_mul_f32 v[10:11], v[10:11], v[44:45] op_sel_hi:[1,0]
	v_pk_mul_f32 v[12:13], v[12:13], v[44:45] op_sel_hi:[1,0]
	v_pk_mul_f32 v[14:15], v[14:15], v[44:45] op_sel_hi:[1,0]
	v_cvt_pk_bf16_f32 v4, v8, v9
	v_cvt_pk_bf16_f32 v5, v10, v11
	v_cvt_pk_bf16_f32 v6, v12, v13
	v_cvt_pk_bf16_f32 v7, v14, v15
	s_nop 1
	v_permlane32_swap_b32_e32 v4, v6
	v_permlane32_swap_b32_e32 v5, v7
	global_store_dwordx4 v[124:125], v[4:7], off offset:352
	s_nop 1
	s_waitcnt lgkmcnt(12)
	v_mfma_f32_32x32x16_bf16 v[0:15], v[108:111], v[116:119], 0
	v_add_u32_e32 v40, v187, v209
	ds_read_b64_tr_b16 v[108:109], v186 offset:63104
	ds_read_b64_tr_b16 v[110:111], v40
	s_waitcnt lgkmcnt(12)
	v_mfma_f32_32x32x16_bf16 v[0:15], v[120:123], v[112:115], v[0:15]
	v_add_u32_e32 v40, v188, v209
	v_add_u32_e32 v42, v189, v209
	ds_read_b64_tr_b16 v[120:121], v40
	ds_read_b64_tr_b16 v[122:123], v42
	s_waitcnt lgkmcnt(12)
	v_mfma_f32_32x32x16_bf16 v[0:15], v[56:59], v[100:103], v[0:15]
	v_add_u32_e32 v40, v190, v209
	v_add_u32_e32 v42, v191, v209
	ds_read_b64_tr_b16 v[56:57], v40
	ds_read_b64_tr_b16 v[58:59], v42
	s_waitcnt lgkmcnt(12)
	v_mfma_f32_32x32x16_bf16 v[0:15], v[60:63], v[96:99], v[0:15]
	v_add_u32_e32 v40, v192, v209
	v_add_u32_e32 v42, v193, v209
	ds_read_b64_tr_b16 v[60:61], v40
	ds_read_b64_tr_b16 v[62:63], v42
	s_waitcnt lgkmcnt(12)
	v_mfma_f32_32x32x16_bf16 v[0:15], v[88:91], v[84:87], v[0:15]
	v_add_u32_e32 v40, v194, v209
	v_add_u32_e32 v42, v195, v209
	ds_read_b64_tr_b16 v[88:89], v40
	ds_read_b64_tr_b16 v[90:91], v42
	s_waitcnt lgkmcnt(12)
	v_mfma_f32_32x32x16_bf16 v[0:15], v[92:95], v[80:83], v[0:15]
	v_add_u32_e32 v40, v196, v209
	v_add_u32_e32 v42, v197, v209
	ds_read_b64_tr_b16 v[92:93], v40
	ds_read_b64_tr_b16 v[94:95], v42
	s_waitcnt lgkmcnt(12)
	v_mfma_f32_32x32x16_bf16 v[0:15], v[104:107], v[68:71], v[0:15]
	v_add_u32_e32 v40, v198, v209
	v_add_u32_e32 v42, v199, v209
	ds_read_b64_tr_b16 v[104:105], v40
	ds_read_b64_tr_b16 v[106:107], v42
	s_waitcnt lgkmcnt(12)
	v_mfma_f32_32x32x16_bf16 v[0:15], v[108:111], v[64:67], v[0:15]
	v_add_u32_e32 v40, v200, v209
	v_add_u32_e32 v42, v201, v209
	ds_read_b64_tr_b16 v[108:109], v40
	ds_read_b64_tr_b16 v[110:111], v42
	s_waitcnt lgkmcnt(12)
	v_mfma_f32_32x32x16_bf16 v[0:15], v[120:123], v[52:55], v[0:15]
	v_add_u32_e32 v40, v202, v209
	v_add_u32_e32 v42, v203, v209
	ds_read_b64_tr_b16 v[120:121], v40
	ds_read_b64_tr_b16 v[122:123], v42
	s_waitcnt lgkmcnt(12)
	v_mfma_f32_32x32x16_bf16 v[0:15], v[56:59], v[48:51], v[0:15]
	ds_read_b64_tr_b16 v[56:57], v186 offset:448
	ds_read_b64_tr_b16 v[58:59], v186 offset:4928
	s_waitcnt lgkmcnt(12)
	v_mfma_f32_32x32x16_bf16 v[0:15], v[60:63], v[36:39], v[0:15]
	ds_read_b64_tr_b16 v[60:61], v186 offset:9408
	ds_read_b64_tr_b16 v[62:63], v186 offset:13888
	s_waitcnt lgkmcnt(12)
	v_mfma_f32_32x32x16_bf16 v[0:15], v[88:91], v[32:35], v[0:15]
	ds_read_b64_tr_b16 v[88:89], v186 offset:18368
	ds_read_b64_tr_b16 v[90:91], v186 offset:22848
	s_waitcnt lgkmcnt(12)
	v_mfma_f32_32x32x16_bf16 v[0:15], v[92:95], v[20:23], v[0:15]
	ds_read_b64_tr_b16 v[92:93], v186 offset:27328
	ds_read_b64_tr_b16 v[94:95], v186 offset:31808
	s_waitcnt lgkmcnt(12)
	v_mfma_f32_32x32x16_bf16 v[0:15], v[104:107], v[16:19], v[0:15]
	ds_read_b64_tr_b16 v[104:105], v186 offset:36288
	ds_read_b64_tr_b16 v[106:107], v186 offset:40768
	s_waitcnt lgkmcnt(12)
	v_mfma_f32_32x32x16_bf16 v[0:15], v[108:111], v[28:31], v[0:15]
	ds_read_b64_tr_b16 v[108:109], v186 offset:45248
	ds_read_b64_tr_b16 v[110:111], v186 offset:49728
	s_waitcnt lgkmcnt(12)
	v_mfma_f32_32x32x16_bf16 v[0:15], v[120:123], v[24:27], v[0:15]
	ds_read_b64_tr_b16 v[120:121], v186 offset:54208
	ds_read_b64_tr_b16 v[122:123], v186 offset:58688
	s_nop 11
	v_pk_mul_f32 v[0:1], v[0:1], v[44:45] op_sel_hi:[1,0]
	v_pk_mul_f32 v[2:3], v[2:3], v[44:45] op_sel_hi:[1,0]
	v_pk_mul_f32 v[4:5], v[4:5], v[44:45] op_sel_hi:[1,0]
	v_pk_mul_f32 v[6:7], v[6:7], v[44:45] op_sel_hi:[1,0]
	v_cvt_pk_bf16_f32 v0, v0, v1
	v_cvt_pk_bf16_f32 v1, v2, v3
	v_cvt_pk_bf16_f32 v2, v4, v5
	v_cvt_pk_bf16_f32 v3, v6, v7
	s_nop 1
	v_permlane32_swap_b32_e32 v0, v2
	v_permlane32_swap_b32_e32 v1, v3
	global_store_dwordx4 v[124:125], v[0:3], off offset:384
	v_pk_mul_f32 v[8:9], v[8:9], v[44:45] op_sel_hi:[1,0]
	v_pk_mul_f32 v[10:11], v[10:11], v[44:45] op_sel_hi:[1,0]
	v_pk_mul_f32 v[12:13], v[12:13], v[44:45] op_sel_hi:[1,0]
	v_pk_mul_f32 v[14:15], v[14:15], v[44:45] op_sel_hi:[1,0]
	v_cvt_pk_bf16_f32 v4, v8, v9
	v_cvt_pk_bf16_f32 v5, v10, v11
	v_cvt_pk_bf16_f32 v6, v12, v13
	v_cvt_pk_bf16_f32 v7, v14, v15
	s_nop 1
	v_permlane32_swap_b32_e32 v4, v6
	v_permlane32_swap_b32_e32 v5, v7
	global_store_dwordx4 v[124:125], v[4:7], off offset:416
	s_nop 1
	s_waitcnt lgkmcnt(12)
	v_mfma_f32_32x32x16_bf16 v[0:15], v[56:59], v[116:119], 0
	v_add_u32_e32 v40, v187, v210
	ds_read_b64_tr_b16 v[56:57], v186 offset:63168
	ds_read_b64_tr_b16 v[58:59], v40
	s_waitcnt lgkmcnt(12)
	v_mfma_f32_32x32x16_bf16 v[0:15], v[60:63], v[112:115], v[0:15]
	v_add_u32_e32 v40, v188, v210
	v_add_u32_e32 v42, v189, v210
	ds_read_b64_tr_b16 v[60:61], v40
	ds_read_b64_tr_b16 v[62:63], v42
	s_waitcnt lgkmcnt(12)
	v_mfma_f32_32x32x16_bf16 v[0:15], v[88:91], v[100:103], v[0:15]
	v_add_u32_e32 v40, v190, v210
	v_add_u32_e32 v42, v191, v210
	ds_read_b64_tr_b16 v[88:89], v40
	ds_read_b64_tr_b16 v[90:91], v42
	s_waitcnt lgkmcnt(12)
	v_mfma_f32_32x32x16_bf16 v[0:15], v[92:95], v[96:99], v[0:15]
	v_add_u32_e32 v40, v192, v210
	v_add_u32_e32 v42, v193, v210
	ds_read_b64_tr_b16 v[92:93], v40
	ds_read_b64_tr_b16 v[94:95], v42
	s_waitcnt lgkmcnt(12)
	v_mfma_f32_32x32x16_bf16 v[0:15], v[104:107], v[84:87], v[0:15]
	v_add_u32_e32 v40, v194, v210
	v_add_u32_e32 v42, v195, v210
	ds_read_b64_tr_b16 v[104:105], v40
	ds_read_b64_tr_b16 v[106:107], v42
	s_waitcnt lgkmcnt(12)
	v_mfma_f32_32x32x16_bf16 v[0:15], v[108:111], v[80:83], v[0:15]
	v_add_u32_e32 v40, v196, v210
	v_add_u32_e32 v42, v197, v210
	ds_read_b64_tr_b16 v[108:109], v40
	ds_read_b64_tr_b16 v[110:111], v42
	s_waitcnt lgkmcnt(12)
	v_mfma_f32_32x32x16_bf16 v[0:15], v[120:123], v[68:71], v[0:15]
	v_add_u32_e32 v40, v198, v210
	v_add_u32_e32 v42, v199, v210
	ds_read_b64_tr_b16 v[120:121], v40
	ds_read_b64_tr_b16 v[122:123], v42
	s_waitcnt lgkmcnt(12)
	v_mfma_f32_32x32x16_bf16 v[0:15], v[56:59], v[64:67], v[0:15]
	v_add_u32_e32 v40, v200, v210
	v_add_u32_e32 v42, v201, v210
	ds_read_b64_tr_b16 v[56:57], v40
	ds_read_b64_tr_b16 v[58:59], v42
	s_waitcnt lgkmcnt(12)
	v_mfma_f32_32x32x16_bf16 v[0:15], v[60:63], v[52:55], v[0:15]
	v_add_u32_e32 v40, v202, v210
	v_add_u32_e32 v42, v203, v210
	ds_read_b64_tr_b16 v[60:61], v40
	ds_read_b64_tr_b16 v[62:63], v42
	s_waitcnt lgkmcnt(12)
	v_mfma_f32_32x32x16_bf16 v[0:15], v[88:91], v[48:51], v[0:15]
	s_waitcnt lgkmcnt(10)
	v_mfma_f32_32x32x16_bf16 v[0:15], v[92:95], v[36:39], v[0:15]
	s_waitcnt lgkmcnt(8)
	v_mfma_f32_32x32x16_bf16 v[0:15], v[104:107], v[32:35], v[0:15]
	s_waitcnt lgkmcnt(6)
	v_mfma_f32_32x32x16_bf16 v[0:15], v[108:111], v[20:23], v[0:15]
	s_waitcnt lgkmcnt(4)
	v_mfma_f32_32x32x16_bf16 v[0:15], v[120:123], v[16:19], v[0:15]
	s_waitcnt lgkmcnt(2)
	v_mfma_f32_32x32x16_bf16 v[0:15], v[56:59], v[28:31], v[0:15]
	s_waitcnt lgkmcnt(0)
	v_mfma_f32_32x32x16_bf16 v[0:15], v[60:63], v[24:27], v[0:15]
	s_nop 11
	v_pk_mul_f32 v[0:1], v[0:1], v[44:45] op_sel_hi:[1,0]
	v_pk_mul_f32 v[2:3], v[2:3], v[44:45] op_sel_hi:[1,0]
	v_pk_mul_f32 v[4:5], v[4:5], v[44:45] op_sel_hi:[1,0]
	v_pk_mul_f32 v[6:7], v[6:7], v[44:45] op_sel_hi:[1,0]
	v_cvt_pk_bf16_f32 v0, v0, v1
	v_cvt_pk_bf16_f32 v1, v2, v3
	v_cvt_pk_bf16_f32 v2, v4, v5
	v_cvt_pk_bf16_f32 v3, v6, v7
	s_nop 1
	v_permlane32_swap_b32_e32 v0, v2
	v_permlane32_swap_b32_e32 v1, v3
	global_store_dwordx4 v[124:125], v[0:3], off offset:448
	v_pk_mul_f32 v[8:9], v[8:9], v[44:45] op_sel_hi:[1,0]
	v_pk_mul_f32 v[10:11], v[10:11], v[44:45] op_sel_hi:[1,0]
	v_pk_mul_f32 v[12:13], v[12:13], v[44:45] op_sel_hi:[1,0]
	v_pk_mul_f32 v[14:15], v[14:15], v[44:45] op_sel_hi:[1,0]
	v_cvt_pk_bf16_f32 v4, v8, v9
	v_cvt_pk_bf16_f32 v5, v10, v11
	v_cvt_pk_bf16_f32 v6, v12, v13
	v_cvt_pk_bf16_f32 v7, v14, v15
	s_nop 1
	v_permlane32_swap_b32_e32 v4, v6
	v_permlane32_swap_b32_e32 v5, v7
	global_store_dwordx4 v[124:125], v[4:7], off offset:480
	s_nop 1
	s_barrier
	s_branch .LBB0_751
